# cache policy: nt on the f32 residual-row loads of the row phases R1/R3/R4 (stream-once data no longer displaces bf16 activations in L2/MALL)
# speedup vs baseline: 1.0149x; 1.0112x over previous
;     ...
;     for (int r = 0; r < NR; ++r)
; #pragma unroll
;         for (int j = 0; j < 4; ++j) x[r][j] = *(const f32x4*)(xin + (size_t)r * DM + j * 256 + lane * 4);
;     ...
;     if (hxout) {
;         float rr[NR];
; #pragma unroll
;         for (int r = 0; r < NR; ++r) { float ss = 0.f;
; #pragma unroll
;             for (int j = 0; j < 4; ++j) ss += (x[r][j][0] * x[r][j][0] + x[r][j][1] * x[r][j][1]) + (x[r][j][2] * x[r][j][2] + x[r][j][3] * x[r][j][3]);
;             rr[r] = ss; }
; #pragma unroll
;         for (int r = 0; r < NR; ++r) rr[r] = rsqrtf(wave_sum(rr[r]) * (1.f / 1024.f) + EPSN);
; #pragma unroll
;         for (int j = 0; j < 4; ++j) { const f32x4 g = *(const f32x4*)(gn + j * 256 + lane * 4) * (*(const f32x4*)(sc + j * 256 + lane * 4) + 1.f), s0 = *(const f32x4*)(sh + j * 256 + lane * 4);
.LBB0_84:
	v_cmp_lt_i32_e32 vcc, v83, v81
	v_mov_b32_e32 v0, v228
	s_ashr_i32 s4, s23, 13
	v_cndmask_b32_e32 v1, v79, v83, vcc
	v_cmp_lt_i32_e32 vcc, v84, v81
	v_lshlrev_b32_e32 v0, 2, v0
	v_lshlrev_b32_e32 v89, 2, v1
	v_cndmask_b32_e32 v2, v79, v84, vcc
	v_cmp_lt_i32_e32 vcc, v85, v81
	v_ashrrev_i32_e32 v1, 31, v0
	v_lshl_add_u64 v[66:67], v[0:1], 1, s[10:11]
	v_cndmask_b32_e32 v3, v79, v85, vcc
	v_cmp_lt_i32_e32 vcc, v86, v81
	s_mulk_i32 s4, 0x1800
	s_ashr_i32 s5, s4, 31
	v_cndmask_b32_e32 v4, v79, v86, vcc
	v_cmp_lt_i32_e32 vcc, v87, v81
	v_lshlrev_b32_e32 v148, 2, v4
	s_lshl_b64 s[4:5], s[4:5], 2
	v_cndmask_b32_e32 v5, v79, v87, vcc
	v_cmp_lt_i32_e32 vcc, v88, v81
	v_lshlrev_b32_e32 v149, 2, v5
	v_lshlrev_b64 v[4:5], 2, v[0:1]
	v_cndmask_b32_e32 v6, v79, v88, vcc
	v_add_co_u32_e32 v68, vcc, s13, v66
	v_lshlrev_b32_e32 v150, 2, v6
	v_lshl_add_u64 v[6:7], s[0:1], 0, v[4:5]
	v_addc_co_u32_e32 v69, vcc, 0, v67, vcc
	v_add_co_u32_e32 v8, vcc, s13, v6
	s_add_u32 s4, s24, s4
	s_nop 0
	v_addc_co_u32_e32 v9, vcc, 0, v7, vcc
	v_add_co_u32_e32 v12, vcc, s18, v6
	s_addc_u32 s5, s25, s5
	s_nop 0
	v_addc_co_u32_e32 v13, vcc, 0, v7, vcc
	v_add_co_u32_e32 v20, vcc, s19, v6
	v_lshl_add_u64 v[72:73], s[4:5], 0, v[4:5]
	s_nop 0
	v_addc_co_u32_e32 v21, vcc, 0, v7, vcc
	v_lshlrev_b32_e32 v146, 2, v2
	v_lshlrev_b32_e32 v147, 2, v3
	global_load_dwordx4 v[48:51], v[6:7], off nt
	global_load_dwordx4 v[44:47], v[6:7], off offset:1024 nt
	global_load_dwordx4 v[16:19], v[6:7], off offset:2048 nt
	global_load_dwordx4 v[0:3], v[6:7], off offset:3072 nt
	v_add_co_u32_e32 v94, vcc, s13, v72
	v_lshl_add_u64 v[70:71], s[28:29], 0, v[4:5]
	s_nop 0
	v_addc_co_u32_e32 v95, vcc, 0, v73, vcc
	global_load_dwordx4 v[90:93], v[70:71], off
	global_load_dwordx4 v[56:59], v[12:13], off offset:-4096 nt
	global_load_dwordx4 v[40:43], v[8:9], off offset:1024 nt
	global_load_dwordx4 v[60:63], v[12:13], off nt
	global_load_dwordx4 v[36:39], v[12:13], off offset:1024 nt
	global_load_dwordx4 v[52:55], v[20:21], off nt
	global_load_dwordx4 v[32:35], v[20:21], off offset:1024 nt
	global_load_dwordx4 v[4:7], v[8:9], off offset:3072 nt
	global_load_dwordx4 v[28:31], v[8:9], off offset:2048 nt
	s_nop 0
	global_load_dwordx4 v[8:11], v[12:13], off offset:3072 nt
	global_load_dwordx4 v[24:27], v[12:13], off offset:2048 nt
	s_nop 0
	global_load_dwordx4 v[12:15], v[20:21], off offset:3072 nt
	s_nop 0
	global_load_dwordx4 v[20:23], v[20:21], off offset:2048 nt
	s_nop 0
	global_load_dwordx4 v[94:97], v[94:95], off
	s_nop 0
	global_load_dwordx4 v[98:101], v[72:73], off
	v_lshl_add_u64 v[74:75], v[72:73], 0, s[14:15]
	s_add_i32 s23, s23, 4
	s_add_u32 s0, s0, 0x4000
	s_addc_u32 s1, s1, 0
	s_add_u32 s10, s10, 0x2000
	s_addc_u32 s11, s11, 0
	s_cmp_ge_i32 s23, s58
	s_waitcnt vmcnt(13)
	v_pk_mul_f32 v[112:113], v[58:59], v[58:59]
	v_pk_mul_f32 v[114:115], v[56:57], v[56:57]
	v_pk_mul_f32 v[102:103], v[50:51], v[50:51]
	v_pk_mul_f32 v[104:105], v[48:49], v[48:49]
	v_pk_mul_f32 v[106:107], v[46:47], v[46:47]
	v_pk_mul_f32 v[108:109], v[44:45], v[44:45]
	v_mul_f32_e32 v76, v17, v17
	v_mul_f32_e32 v78, v19, v19
	v_mul_f32_e32 v139, v2, v2
	v_mul_f32_e32 v141, v3, v3
	v_pk_mov_b32 v[110:111], v[104:105], v[102:103] op_sel:[1,0]
	v_mov_b32_e32 v105, v103
	v_pk_mov_b32 v[102:103], v[108:109], v[106:107] op_sel:[1,0]
	v_mov_b32_e32 v109, v107
	v_pk_fma_f32 v[106:107], v[16:17], v[16:17], v[76:77] op_sel_hi:[1,1,0]
	s_waitcnt vmcnt(12)
	v_pk_mul_f32 v[116:117], v[42:43], v[42:43]
	v_pk_mul_f32 v[118:119], v[40:41], v[40:41]
	v_pk_fma_f32 v[136:137], v[18:19], v[18:19], v[78:79] op_sel_hi:[1,1,0]
	s_waitcnt vmcnt(11)
	v_pk_mul_f32 v[120:121], v[62:63], v[62:63]
	v_pk_mul_f32 v[122:123], v[60:61], v[60:61]
	s_waitcnt vmcnt(10)
	v_pk_mul_f32 v[124:125], v[38:39], v[38:39]
	v_pk_mul_f32 v[126:127], v[36:37], v[36:37]
	s_waitcnt vmcnt(9)
	v_pk_mul_f32 v[128:129], v[54:55], v[54:55]
	v_pk_mul_f32 v[130:131], v[52:53], v[52:53]
	s_waitcnt vmcnt(8)
	v_pk_mul_f32 v[132:133], v[34:35], v[34:35]
	v_pk_mul_f32 v[134:135], v[32:33], v[32:33]
	s_waitcnt vmcnt(1)
	v_pk_add_f32 v[96:97], v[96:97], 1.0 op_sel_hi:[1,0]
	v_pk_add_f32 v[94:95], v[94:95], 1.0 op_sel_hi:[1,0]
	v_pk_add_f32 v[104:105], v[110:111], v[104:105]
	v_pk_add_f32 v[102:103], v[102:103], v[108:109]
	v_mov_b32_e32 v107, v139
	v_pk_mov_b32 v[108:109], v[114:115], v[112:113] op_sel:[1,0]
	v_mov_b32_e32 v115, v113
	v_pk_mov_b32 v[110:111], v[118:119], v[116:117] op_sel:[1,0]
	v_mov_b32_e32 v119, v117
	v_mov_b32_e32 v137, v141
	v_mul_f32_e32 v76, v29, v29
	v_mul_f32_e32 v78, v31, v31
	v_pk_mov_b32 v[112:113], v[122:123], v[120:121] op_sel:[1,0]
	v_mov_b32_e32 v123, v121
	v_pk_mov_b32 v[116:117], v[126:127], v[124:125] op_sel:[1,0]
	v_mov_b32_e32 v127, v125
	v_pk_mov_b32 v[120:121], v[130:131], v[128:129] op_sel:[1,0]
	v_mov_b32_e32 v131, v129
	v_pk_mov_b32 v[124:125], v[134:135], v[132:133] op_sel:[1,0]
	v_mov_b32_e32 v135, v133
	v_pk_mul_f32 v[92:93], v[92:93], v[96:97]
	v_pk_mul_f32 v[90:91], v[90:91], v[94:95]
	v_pk_add_f32 v[94:95], v[106:107], v[136:137]
	v_pk_add_f32 v[96:97], v[108:109], v[114:115]
	v_pk_add_f32 v[106:107], v[110:111], v[118:119]
	v_mul_f32_e32 v151, v0, v0
	v_mul_f32_e32 v152, v1, v1
	v_mul_f32_e32 v153, v6, v6
	v_mul_f32_e32 v154, v7, v7
	v_mul_f32_e32 v80, v25, v25
	v_mul_f32_e32 v82, v27, v27
	v_mul_f32_e32 v138, v21, v21
	v_mul_f32_e32 v140, v23, v23
	v_mul_f32_e32 v159, v4, v4
	v_mul_f32_e32 v160, v5, v5
	v_pk_fma_f32 v[128:129], v[28:29], v[28:29], v[76:77] op_sel_hi:[1,1,0]
	v_pk_fma_f32 v[132:133], v[30:31], v[30:31], v[78:79] op_sel_hi:[1,1,0]
	v_pk_add_f32 v[108:109], v[112:113], v[122:123]
	v_pk_add_f32 v[110:111], v[116:117], v[126:127]
; __device__ __forceinline__ unsigned cvt_pk_bf16(float lo, float hi) { unsigned r; asm volatile("v_cvt_pk_bf16_f32 %0, %1, %2" : "=v"(r) : "v"(lo), "v"(hi)); return r; }
; __device__ __forceinline__ float wave_sum(float v) {
; #pragma unroll
;     for (int o = 1; o < 64; o <<= 1) v += __shfl_xor(v, o);
;     return v;
;     ...
; #pragma unroll
;         for (int r = 0; r < NR; ++r) rr[r] = rsqrtf(wave_sum(rr[r]) * (1.f / 1024.f) + EPSN);
; #pragma unroll
;         for (int j = 0; j < 4; ++j) { const f32x4 g = *(const f32x4*)(gn + j * 256 + lane * 4) * (*(const f32x4*)(sc + j * 256 + lane * 4) + 1.f), s0 = *(const f32x4*)(sh + j * 256 + lane * 4);
; #pragma unroll
;             for (int r = 0; r < NR; ++r) { const f32x4 h = (x[r][j] * rr[r]) * g + s0; v2u w; w.x = cvt_pk_bf16(h[0], h[1]); w.y = cvt_pk_bf16(h[2], h[3]); *(v2u*)(hxout + (size_t)r * DM + j * 256 + lane * 4) = w; } }
	v_pk_add_f32 v[112:113], v[120:121], v[130:131]
	v_pk_add_f32 v[114:115], v[124:125], v[134:135]
	v_pk_add_f32 v[104:105], v[104:105], v[104:105] op_sel:[0,1] op_sel_hi:[1,0]
	v_pk_add_f32 v[102:103], v[102:103], v[102:103] op_sel:[0,1] op_sel_hi:[1,0]
	v_pk_add_f32 v[96:97], v[96:97], v[96:97] op_sel:[0,1] op_sel_hi:[1,0]
	v_pk_add_f32 v[106:107], v[106:107], v[106:107] op_sel:[0,1] op_sel_hi:[1,0]
	v_mul_f32_e32 v155, v10, v10
	v_mul_f32_e32 v156, v11, v11
	v_mul_f32_e32 v157, v14, v14
	v_mul_f32_e32 v158, v15, v15
	v_mul_f32_e32 v161, v8, v8
	v_mul_f32_e32 v162, v9, v9
	v_mul_f32_e32 v163, v12, v12
	v_mul_f32_e32 v164, v13, v13
	v_pk_fma_f32 v[142:143], v[24:25], v[24:25], v[80:81] op_sel_hi:[1,1,0]
	v_pk_fma_f32 v[144:145], v[26:27], v[26:27], v[82:83] op_sel_hi:[1,1,0]
	v_pk_fma_f32 v[138:139], v[20:21], v[20:21], v[138:139] op_sel_hi:[1,1,0]
	v_pk_fma_f32 v[140:141], v[22:23], v[22:23], v[140:141] op_sel_hi:[1,1,0]
	v_mov_b32_e32 v129, v153
	v_mov_b32_e32 v133, v154
	v_mov_b32_e32 v105, v151
	v_mov_b32_e32 v103, v152
	v_pk_add_f32 v[108:109], v[108:109], v[108:109] op_sel:[0,1] op_sel_hi:[1,0]
	v_pk_add_f32 v[110:111], v[110:111], v[110:111] op_sel:[0,1] op_sel_hi:[1,0]
	v_pk_add_f32 v[112:113], v[112:113], v[112:113] op_sel:[0,1] op_sel_hi:[1,0]
	v_pk_add_f32 v[114:115], v[114:115], v[114:115] op_sel:[0,1] op_sel_hi:[1,0]
	v_mov_b32_e32 v97, v159
	v_mov_b32_e32 v107, v160
	v_mov_b32_e32 v143, v155
	v_mov_b32_e32 v145, v156
	v_mov_b32_e32 v139, v157
	v_mov_b32_e32 v141, v158
	v_pk_add_f32 v[116:117], v[128:129], v[132:133]
	v_pk_add_f32 v[102:103], v[104:105], v[102:103]
	v_mov_b32_e32 v109, v161
	v_mov_b32_e32 v111, v162
	v_mov_b32_e32 v113, v163
	v_mov_b32_e32 v115, v164
	v_pk_add_f32 v[96:97], v[96:97], v[106:107]
	v_pk_add_f32 v[118:119], v[142:143], v[144:145]
	v_pk_add_f32 v[120:121], v[138:139], v[140:141]
	v_pk_add_f32 v[94:95], v[102:103], v[94:95]
	v_pk_add_f32 v[102:103], v[108:109], v[110:111]
	v_pk_add_f32 v[104:105], v[112:113], v[114:115]
	v_pk_add_f32 v[96:97], v[96:97], v[116:117]
	v_pk_add_f32 v[102:103], v[102:103], v[118:119]
	v_pk_add_f32 v[104:105], v[104:105], v[120:121]
	v_mov_b32_e32 v107, v94
	v_mov_b32_e32 v106, v96
	v_mov_b32_e32 v94, v97
	v_mov_b32_e32 v96, v104
	v_mov_b32_e32 v97, v102
	v_mov_b32_e32 v102, v105
	v_pk_add_f32 v[94:95], v[106:107], v[94:95]
	v_pk_add_f32 v[96:97], v[96:97], v[102:103]
	ds_bpermute_b32 v103, v89, v95
	ds_bpermute_b32 v102, v89, v94
	ds_bpermute_b32 v105, v89, v97
	ds_bpermute_b32 v104, v89, v96
	s_waitcnt lgkmcnt(2)
	v_pk_add_f32 v[94:95], v[94:95], v[102:103]
	ds_bpermute_b32 v103, v146, v95
	ds_bpermute_b32 v102, v146, v94
	s_waitcnt lgkmcnt(2)
	v_pk_add_f32 v[96:97], v[96:97], v[104:105]
	ds_bpermute_b32 v105, v146, v97
	ds_bpermute_b32 v104, v146, v96
	s_waitcnt lgkmcnt(2)
	v_pk_add_f32 v[94:95], v[94:95], v[102:103]
	ds_bpermute_b32 v103, v147, v95
	ds_bpermute_b32 v102, v147, v94
	s_waitcnt lgkmcnt(2)
	v_pk_add_f32 v[96:97], v[96:97], v[104:105]
	ds_bpermute_b32 v105, v147, v97
	ds_bpermute_b32 v104, v147, v96
	s_waitcnt lgkmcnt(2)
	v_pk_add_f32 v[94:95], v[94:95], v[102:103]
	ds_bpermute_b32 v103, v148, v95
	ds_bpermute_b32 v102, v148, v94
	s_waitcnt lgkmcnt(2)
	v_pk_add_f32 v[96:97], v[96:97], v[104:105]
	ds_bpermute_b32 v105, v148, v97
	ds_bpermute_b32 v104, v148, v96
	s_waitcnt lgkmcnt(2)
	v_pk_add_f32 v[94:95], v[94:95], v[102:103]
	ds_bpermute_b32 v103, v149, v95
	ds_bpermute_b32 v102, v149, v94
	s_waitcnt lgkmcnt(2)
	v_pk_add_f32 v[96:97], v[96:97], v[104:105]
	ds_bpermute_b32 v105, v149, v97
	ds_bpermute_b32 v104, v149, v96
	s_waitcnt lgkmcnt(2)
	v_pk_add_f32 v[94:95], v[94:95], v[102:103]
	ds_bpermute_b32 v103, v150, v95
	ds_bpermute_b32 v102, v150, v94
	s_waitcnt lgkmcnt(2)
	v_pk_add_f32 v[96:97], v[96:97], v[104:105]
	ds_bpermute_b32 v105, v150, v97
	ds_bpermute_b32 v104, v150, v96
	s_waitcnt lgkmcnt(2)
	v_pk_add_f32 v[94:95], v[94:95], v[102:103]
	s_nop 0
	v_pk_fma_f32 v[94:95], v[94:95], s[12:13], v[64:65] op_sel_hi:[1,0,0]
	s_waitcnt lgkmcnt(0)
	v_pk_add_f32 v[96:97], v[96:97], v[104:105]
	v_mul_f32_e32 v76, 0x4b800000, v95
	v_cmp_gt_f32_e64 s[8:9], s22, v95
	v_pk_fma_f32 v[96:97], v[96:97], s[12:13], v[64:65] op_sel_hi:[1,0,0]
	v_mul_f32_e32 v78, 0x4b800000, v94
	v_cndmask_b32_e64 v76, v95, v76, s[8:9]
	v_cmp_gt_f32_e32 vcc, s22, v94
	v_rsq_f32_e32 v76, v76
	v_mul_f32_e32 v80, 0x4b800000, v97
	v_cmp_gt_f32_e64 s[6:7], s22, v97
	v_cndmask_b32_e32 v78, v94, v78, vcc
	v_mul_f32_e32 v82, 0x4b800000, v96
	v_cmp_gt_f32_e64 s[4:5], s22, v96
	v_cndmask_b32_e64 v80, v97, v80, s[6:7]
	v_rsq_f32_e32 v78, v78
	v_cndmask_b32_e64 v82, v96, v82, s[4:5]
	v_rsq_f32_e32 v89, v80
	v_rsq_f32_e32 v94, v82
	v_mul_f32_e32 v80, 0x45800000, v76
	v_cndmask_b32_e64 v82, v76, v80, s[8:9]
	v_mul_f32_e32 v95, 0x45800000, v78
	v_pk_mul_f32 v[48:49], v[48:49], v[82:83] op_sel_hi:[1,0]
	v_mul_f32_e32 v96, 0x45800000, v89
	v_cndmask_b32_e32 v80, v78, v95, vcc
	v_pk_mul_f32 v[50:51], v[50:51], v[82:83] op_sel_hi:[1,0]
	s_waitcnt vmcnt(0)
; __device__ __forceinline__ unsigned cvt_pk_bf16(float lo, float hi) { unsigned r; asm volatile("v_cvt_pk_bf16_f32 %0, %1, %2" : "=v"(r) : "v"(lo), "v"(hi)); return r; }
;     ...
; #pragma unroll
;         for (int j = 0; j < 4; ++j) { const f32x4 g = *(const f32x4*)(gn + j * 256 + lane * 4) * (*(const f32x4*)(sc + j * 256 + lane * 4) + 1.f), s0 = *(const f32x4*)(sh + j * 256 + lane * 4);
; #pragma unroll
;             for (int r = 0; r < NR; ++r) { const f32x4 h = (x[r][j] * rr[r]) * g + s0; v2u w; w.x = cvt_pk_bf16(h[0], h[1]); w.y = cvt_pk_bf16(h[2], h[3]); *(v2u*)(hxout + (size_t)r * DM + j * 256 + lane * 4) = w; } }
; __global__ void __launch_bounds__(512, 2) fwd_megakernel(Args a) {
;     ...
;     for (int row = gw * (ML / NGW), rend = row + ML / NGW; row < rend; row += 4) {
;         const float* md = MOD + (size_t)(row >> 13) * 6144;
;         row_op<4>(a.in[0] + (size_t)row * DM, nullptr, nullptr, nullptr, nullptr, HX + (size_t)row * DM, a.in[6], md + 1024, md, lane);
;     }
	v_pk_fma_f32 v[48:49], v[48:49], v[90:91], v[98:99]
	v_mul_f32_e32 v97, 0x45800000, v94
	v_cndmask_b32_e64 v78, v89, v96, s[6:7]
	v_pk_mul_f32 v[56:57], v[56:57], v[80:81] op_sel_hi:[1,0]
	v_pk_mul_f32 v[58:59], v[58:59], v[80:81] op_sel_hi:[1,0]
	v_pk_fma_f32 v[50:51], v[50:51], v[92:93], v[100:101]
	v_cvt_pk_bf16_f32 v48, v48, v49
	v_cndmask_b32_e64 v76, v94, v97, s[4:5]
	v_cvt_pk_bf16_f32 v49, v50, v51
	v_pk_mul_f32 v[60:61], v[60:61], v[78:79] op_sel_hi:[1,0]
	v_pk_mul_f32 v[62:63], v[62:63], v[78:79] op_sel_hi:[1,0]
	v_pk_fma_f32 v[58:59], v[58:59], v[92:93], v[100:101]
	v_pk_fma_f32 v[56:57], v[56:57], v[90:91], v[98:99]
	global_store_dwordx2 v[66:67], v[48:49], off
	v_cvt_pk_bf16_f32 v48, v56, v57
	v_cvt_pk_bf16_f32 v49, v58, v59
	v_pk_mul_f32 v[52:53], v[52:53], v[76:77] op_sel_hi:[1,0]
	v_pk_mul_f32 v[54:55], v[54:55], v[76:77] op_sel_hi:[1,0]
	v_pk_fma_f32 v[62:63], v[92:93], v[62:63], v[100:101]
	v_pk_fma_f32 v[60:61], v[90:91], v[60:61], v[98:99]
	global_store_dwordx2 v[66:67], v[48:49], off offset:2048
	v_cvt_pk_bf16_f32 v48, v60, v61
	v_cvt_pk_bf16_f32 v49, v62, v63
	v_pk_fma_f32 v[54:55], v[92:93], v[54:55], v[100:101]
	v_pk_fma_f32 v[52:53], v[90:91], v[52:53], v[98:99]
	global_store_dwordx2 v[68:69], v[48:49], off
	v_cvt_pk_bf16_f32 v48, v52, v53
	v_cvt_pk_bf16_f32 v49, v54, v55
	global_store_dwordx2 v[68:69], v[48:49], off offset:2048
	global_load_dwordx4 v[48:51], v[74:75], off offset:1024
	s_nop 0
	global_load_dwordx4 v[52:55], v[70:71], off offset:1024
	global_load_dwordx4 v[56:59], v[72:73], off offset:1024
	v_pk_mul_f32 v[44:45], v[44:45], v[82:83] op_sel_hi:[1,0]
	v_pk_mul_f32 v[40:41], v[40:41], v[80:81] op_sel_hi:[1,0]
	v_pk_mul_f32 v[36:37], v[36:37], v[78:79] op_sel_hi:[1,0]
	v_pk_mul_f32 v[32:33], v[32:33], v[76:77] op_sel_hi:[1,0]
	v_pk_mul_f32 v[46:47], v[46:47], v[82:83] op_sel_hi:[1,0]
	v_pk_mul_f32 v[42:43], v[42:43], v[80:81] op_sel_hi:[1,0]
	v_pk_mul_f32 v[38:39], v[38:39], v[78:79] op_sel_hi:[1,0]
	v_pk_mul_f32 v[34:35], v[34:35], v[76:77] op_sel_hi:[1,0]
	v_pk_mul_f32 v[16:17], v[16:17], v[82:83] op_sel_hi:[1,0]
	v_pk_mul_f32 v[18:19], v[18:19], v[82:83] op_sel_hi:[1,0]
	v_pk_mul_f32 v[28:29], v[28:29], v[80:81] op_sel_hi:[1,0]
	v_pk_mul_f32 v[30:31], v[30:31], v[80:81] op_sel_hi:[1,0]
	v_pk_mul_f32 v[24:25], v[24:25], v[78:79] op_sel_hi:[1,0]
	v_pk_mul_f32 v[26:27], v[26:27], v[78:79] op_sel_hi:[1,0]
	v_pk_mul_f32 v[20:21], v[20:21], v[76:77] op_sel_hi:[1,0]
	v_pk_mul_f32 v[22:23], v[22:23], v[76:77] op_sel_hi:[1,0]
	v_pk_mul_f32 v[0:1], v[0:1], v[82:83] op_sel_hi:[1,0]
	v_pk_mul_f32 v[2:3], v[2:3], v[82:83] op_sel_hi:[1,0]
	v_pk_mul_f32 v[4:5], v[4:5], v[80:81] op_sel_hi:[1,0]
	v_pk_mul_f32 v[6:7], v[6:7], v[80:81] op_sel_hi:[1,0]
	v_pk_mul_f32 v[8:9], v[8:9], v[78:79] op_sel_hi:[1,0]
	v_pk_mul_f32 v[10:11], v[10:11], v[78:79] op_sel_hi:[1,0]
	v_pk_mul_f32 v[12:13], v[12:13], v[76:77] op_sel_hi:[1,0]
	v_pk_mul_f32 v[14:15], v[14:15], v[76:77] op_sel_hi:[1,0]
	s_waitcnt vmcnt(2)
	v_pk_add_f32 v[48:49], v[48:49], 1.0 op_sel_hi:[1,0]
	v_pk_add_f32 v[50:51], v[50:51], 1.0 op_sel_hi:[1,0]
	s_waitcnt vmcnt(1)
	v_pk_mul_f32 v[48:49], v[52:53], v[48:49]
	v_pk_mul_f32 v[50:51], v[54:55], v[50:51]
	s_waitcnt vmcnt(0)
	v_pk_fma_f32 v[44:45], v[44:45], v[48:49], v[56:57]
	v_pk_fma_f32 v[40:41], v[40:41], v[48:49], v[56:57]
	v_pk_fma_f32 v[36:37], v[36:37], v[48:49], v[56:57]
	v_pk_fma_f32 v[32:33], v[32:33], v[48:49], v[56:57]
	v_pk_fma_f32 v[46:47], v[46:47], v[50:51], v[58:59]
	v_pk_fma_f32 v[42:43], v[42:43], v[50:51], v[58:59]
	v_pk_fma_f32 v[38:39], v[38:39], v[50:51], v[58:59]
	v_pk_fma_f32 v[34:35], v[34:35], v[50:51], v[58:59]
	v_cvt_pk_bf16_f32 v44, v44, v45
	v_cvt_pk_bf16_f32 v45, v46, v47
	global_store_dwordx2 v[66:67], v[44:45], off offset:512
	v_cvt_pk_bf16_f32 v40, v40, v41
	v_cvt_pk_bf16_f32 v41, v42, v43
	global_store_dwordx2 v[66:67], v[40:41], off offset:2560
	v_cvt_pk_bf16_f32 v36, v36, v37
	v_cvt_pk_bf16_f32 v37, v38, v39
	global_store_dwordx2 v[68:69], v[36:37], off offset:512
	v_cvt_pk_bf16_f32 v32, v32, v33
	v_cvt_pk_bf16_f32 v33, v34, v35
	global_store_dwordx2 v[68:69], v[32:33], off offset:2560
	global_load_dwordx4 v[32:35], v[74:75], off offset:2048
	s_nop 0
	global_load_dwordx4 v[36:39], v[70:71], off offset:2048
	global_load_dwordx4 v[40:43], v[72:73], off offset:2048
	s_waitcnt vmcnt(2)
	v_pk_add_f32 v[32:33], v[32:33], 1.0 op_sel_hi:[1,0]
	v_pk_add_f32 v[34:35], v[34:35], 1.0 op_sel_hi:[1,0]
	s_waitcnt vmcnt(1)
	v_pk_mul_f32 v[32:33], v[36:37], v[32:33]
	v_pk_mul_f32 v[34:35], v[38:39], v[34:35]
	s_waitcnt vmcnt(0)
	v_pk_fma_f32 v[16:17], v[16:17], v[32:33], v[40:41]
	v_pk_fma_f32 v[18:19], v[18:19], v[34:35], v[42:43]
	v_cvt_pk_bf16_f32 v16, v16, v17
	v_pk_fma_f32 v[30:31], v[30:31], v[34:35], v[42:43]
	v_cvt_pk_bf16_f32 v17, v18, v19
	v_pk_fma_f32 v[28:29], v[28:29], v[32:33], v[40:41]
	global_store_dwordx2 v[66:67], v[16:17], off offset:1024
	v_cvt_pk_bf16_f32 v16, v28, v29
	v_cvt_pk_bf16_f32 v17, v30, v31
	v_pk_fma_f32 v[26:27], v[26:27], v[34:35], v[42:43]
	v_pk_fma_f32 v[24:25], v[24:25], v[32:33], v[40:41]
	global_store_dwordx2 v[66:67], v[16:17], off offset:3072
	v_cvt_pk_bf16_f32 v16, v24, v25
	v_cvt_pk_bf16_f32 v17, v26, v27
	v_pk_fma_f32 v[22:23], v[22:23], v[34:35], v[42:43]
	v_pk_fma_f32 v[20:21], v[20:21], v[32:33], v[40:41]
	global_store_dwordx2 v[68:69], v[16:17], off offset:1024
	v_cvt_pk_bf16_f32 v16, v20, v21
	v_cvt_pk_bf16_f32 v17, v22, v23
	global_store_dwordx2 v[68:69], v[16:17], off offset:3072
	global_load_dwordx4 v[16:19], v[74:75], off offset:3072
	s_nop 0
	global_load_dwordx4 v[20:23], v[70:71], off offset:3072
	global_load_dwordx4 v[24:27], v[72:73], off offset:3072
	s_waitcnt vmcnt(2)
	v_pk_add_f32 v[16:17], v[16:17], 1.0 op_sel_hi:[1,0]
	v_pk_add_f32 v[18:19], v[18:19], 1.0 op_sel_hi:[1,0]
	s_waitcnt vmcnt(1)
	v_pk_mul_f32 v[16:17], v[20:21], v[16:17]
	v_pk_mul_f32 v[18:19], v[22:23], v[18:19]
	s_waitcnt vmcnt(0)
	v_pk_fma_f32 v[0:1], v[0:1], v[16:17], v[24:25]
	v_pk_fma_f32 v[2:3], v[2:3], v[18:19], v[26:27]
	v_cvt_pk_bf16_f32 v0, v0, v1
	v_pk_fma_f32 v[6:7], v[6:7], v[18:19], v[26:27]
	v_cvt_pk_bf16_f32 v1, v2, v3
	v_pk_fma_f32 v[4:5], v[4:5], v[16:17], v[24:25]
	global_store_dwordx2 v[66:67], v[0:1], off offset:1536
	v_cvt_pk_bf16_f32 v0, v4, v5
	v_cvt_pk_bf16_f32 v1, v6, v7
	v_pk_fma_f32 v[10:11], v[10:11], v[18:19], v[26:27]
	v_pk_fma_f32 v[8:9], v[8:9], v[16:17], v[24:25]
	global_store_dwordx2 v[66:67], v[0:1], off offset:3584
	v_cvt_pk_bf16_f32 v0, v8, v9
	v_cvt_pk_bf16_f32 v1, v10, v11
	v_pk_fma_f32 v[14:15], v[14:15], v[18:19], v[26:27]
	v_pk_fma_f32 v[12:13], v[12:13], v[16:17], v[24:25]
	global_store_dwordx2 v[68:69], v[0:1], off offset:1536
	v_cvt_pk_bf16_f32 v0, v12, v13
	v_cvt_pk_bf16_f32 v1, v14, v15
	global_store_dwordx2 v[68:69], v[0:1], off offset:3584
	s_cbranch_scc0 .LBB0_84

;     ...
;     f32x4 x[NR][4];
; #pragma unroll
;     for (int r = 0; r < NR; ++r)
; #pragma unroll
;         for (int j = 0; j < 4; ++j) x[r][j] = *(const f32x4*)(xin + (size_t)r * DM + j * 256 + lane * 4);
;     if (upd) {
;         f32x4 y[NR][4];
; #pragma unroll
;         for (int r = 0; r < NR; ++r)
; #pragma unroll
;             for (int j = 0; j < 4; ++j) {
;                 if (NP == 0) { const v2u w = *(const v2u*)(upd + (size_t)r * DM + j * 256 + lane * 4); y[r][j][0] = bflo(w.x); y[r][j][1] = bfhi(w.x); y[r][j][2] = bflo(w.y); y[r][j][3] = bfhi(w.y); }
;                 else { const float* pp = (const float*)upd + (size_t)r * DM + j * 256 + lane * 4; f32x4 t = *(const f32x4*)pp;
; #pragma unroll
;                     for (int p = 1; p < NP; ++p) t = t + *(const f32x4*)(pp + (size_t)p * 2048 * 1024);
;                     y[r][j] = t; } }
;         float rr[NR];
; #pragma unroll
;         for (int r = 0; r < NR; ++r) { float ss = 0.f;
; #pragma unroll
;             for (int j = 0; j < 4; ++j) ss += (y[r][j][0] * y[r][j][0] + y[r][j][1] * y[r][j][1]) + (y[r][j][2] * y[r][j][2] + y[r][j][3] * y[r][j][3]);
;             rr[r] = ss; }
.LBB0_653:
	v_mov_b32_e32 v0, v228
	s_ashr_i32 s5, s4, 13
	v_lshlrev_b32_e32 v64, 2, v0
	v_ashrrev_i32_e32 v65, 31, v64
	v_lshlrev_b64 v[86:87], 2, v[64:65]
	v_lshl_add_u64 v[12:13], s[34:35], 0, v[86:87]
	v_add_co_u32_e32 v4, vcc, s75, v12
	global_load_dwordx4 v[48:51], v[12:13], off nt
	global_load_dwordx4 v[40:43], v[12:13], off offset:1024 nt
	global_load_dwordx4 v[16:19], v[12:13], off offset:2048 nt
	global_load_dwordx4 v[0:3], v[12:13], off offset:3072 nt
	v_addc_co_u32_e32 v5, vcc, 0, v13, vcc
	v_add_co_u32_e32 v6, vcc, s28, v12
	v_lshl_add_u64 v[64:65], v[64:65], 1, s[36:37]
	s_nop 0
	v_addc_co_u32_e32 v7, vcc, 0, v13, vcc
	v_add_co_u32_e32 v12, vcc, s38, v12
	global_load_dwordx4 v[52:55], v[6:7], off offset:-4096 nt
	global_load_dwordx4 v[44:47], v[4:5], off offset:1024 nt
	global_load_dwordx4 v[20:23], v[4:5], off offset:2048 nt
	global_load_dwordx4 v[8:11], v[4:5], off offset:3072 nt
	global_load_dwordx4 v[56:59], v[6:7], off nt
	global_load_dwordx4 v[36:39], v[6:7], off offset:1024 nt
	global_load_dwordx4 v[24:27], v[6:7], off offset:2048 nt
	s_nop 0
	global_load_dwordx4 v[4:7], v[6:7], off offset:3072 nt
	v_addc_co_u32_e32 v13, vcc, 0, v13, vcc
	global_load_dwordx4 v[60:63], v[12:13], off nt
	global_load_dwordx4 v[32:35], v[12:13], off offset:1024 nt
	global_load_dwordx4 v[28:31], v[12:13], off offset:2048 nt
	s_nop 0
	global_load_dwordx4 v[12:15], v[12:13], off offset:3072 nt
	s_nop 0
	global_load_dwordx2 v[68:69], v[64:65], off
	global_load_dwordx2 v[70:71], v[64:65], off offset:512
	global_load_dwordx2 v[72:73], v[64:65], off offset:1024
	global_load_dwordx2 v[66:67], v[64:65], off offset:1536
	s_mul_i32 s6, s5, 0x1800
	s_ashr_i32 s7, s6, 31
	s_lshl_b64 s[6:7], s[6:7], 2
	s_add_u32 s40, s42, s6
	s_addc_u32 s41, s43, s7
	v_lshl_add_u64 v[156:157], s[0:1], 0, v[86:87]
	s_movk_i32 s5, 0x4000
	s_mov_b64 s[6:7], 0x4000
	s_add_i32 s4, s4, 4
	s_add_u32 s36, s36, 0x2000
	s_addc_u32 s37, s37, 0
	s_add_u32 s34, s34, 0x4000
	s_addc_u32 s35, s35, 0
	s_cmp_ge_i32 s4, s58
	s_waitcnt vmcnt(2)
	v_and_b32_e32 v119, 0xffff0000, v71
	v_and_b32_e32 v118, 0xffff0000, v70
	s_waitcnt vmcnt(0)
	v_lshlrev_b32_e32 v93, 16, v66
	v_and_b32_e32 v91, 0xffff0000, v66
	v_lshlrev_b32_e32 v88, 16, v67
	v_and_b32_e32 v89, 0xffff0000, v67
	global_load_dwordx2 v[74:75], v[64:65], off offset:2048
	global_load_dwordx2 v[76:77], v[64:65], off offset:2560
	global_load_dwordx2 v[80:81], v[64:65], off offset:3072
	global_load_dwordx2 v[66:67], v[64:65], off offset:3584
	v_lshlrev_b32_e32 v112, 16, v72
	v_and_b32_e32 v113, 0xffff0000, v72
	v_lshlrev_b32_e32 v117, 16, v71
	v_lshlrev_b32_e32 v116, 16, v70
	v_pk_mul_f32 v[70:71], v[118:119], v[118:119]
	v_lshlrev_b32_e32 v114, 16, v73
	v_and_b32_e32 v115, 0xffff0000, v73
	v_pk_fma_f32 v[70:71], v[116:117], v[116:117], v[70:71]
	v_mov_b32_e32 v121, v93
	v_mul_f32_e32 v90, v91, v91
	v_pk_add_f32 v[70:71], v[70:71], v[70:71] op_sel:[0,1] op_sel_hi:[1,0]
	v_mul_f32_e32 v96, v88, v88
	v_mov_b32_e32 v71, v90
	v_mul_f32_e32 v98, v89, v89
	s_waitcnt vmcnt(2)
	v_and_b32_e32 v127, 0xffff0000, v77
	v_and_b32_e32 v126, 0xffff0000, v76
	s_waitcnt vmcnt(0)
	v_lshlrev_b32_e32 v99, 16, v66
	v_and_b32_e32 v97, 0xffff0000, v66
	v_add_co_u32_e32 v66, vcc, s75, v64
	v_lshlrev_b32_e32 v94, 16, v67
	v_and_b32_e32 v95, 0xffff0000, v67
	v_addc_co_u32_e32 v67, vcc, 0, v65, vcc
	global_load_dwordx2 v[82:83], v[66:67], off
	global_load_dwordx2 v[84:85], v[66:67], off offset:512
	global_load_dwordx2 v[130:131], v[66:67], off offset:1024
	global_load_dwordx2 v[78:79], v[66:67], off offset:1536
	global_load_dwordx2 v[136:137], v[66:67], off offset:2048
	global_load_dwordx2 v[138:139], v[66:67], off offset:2560
	global_load_dwordx2 v[152:153], v[66:67], off offset:3072
	s_nop 0
	global_load_dwordx2 v[66:67], v[66:67], off offset:3584
	v_lshlrev_b32_e32 v125, 16, v77
	v_lshlrev_b32_e32 v124, 16, v76
	v_pk_mul_f32 v[76:77], v[126:127], v[126:127]
	v_lshlrev_b32_e32 v122, 16, v81
	v_and_b32_e32 v123, 0xffff0000, v81
	v_pk_fma_f32 v[76:77], v[124:125], v[124:125], v[76:77]
	v_mov_b32_e32 v129, v99
	v_mul_f32_e32 v90, v97, v97
	v_pk_add_f32 v[76:77], v[76:77], v[76:77] op_sel:[0,1] op_sel_hi:[1,0]
	s_waitcnt vmcnt(7)
	v_and_b32_e32 v141, 0xffff0000, v82
	v_mov_b32_e32 v77, v90
	v_and_b32_e32 v143, 0xffff0000, v83
	s_waitcnt vmcnt(4)
	v_lshlrev_b32_e32 v105, 16, v78
	s_waitcnt vmcnt(0)
; __device__ __forceinline__ float wave_sum(float v) {
; #pragma unroll
;     for (int o = 1; o < 64; o <<= 1) v += __shfl_xor(v, o);
;     return v;
;     ...
;         float rr[NR];
; #pragma unroll
;         for (int r = 0; r < NR; ++r) { float ss = 0.f;
; #pragma unroll
;             for (int j = 0; j < 4; ++j) ss += (y[r][j][0] * y[r][j][0] + y[r][j][1] * y[r][j][1]) + (y[r][j][2] * y[r][j][2] + y[r][j][3] * y[r][j][3]);
;             rr[r] = ss; }
; #pragma unroll
;         for (int r = 0; r < NR; ++r) rr[r] = rsqrtf(wave_sum(rr[r]) * (1.f / 1024.f) + EPSN);
	v_lshlrev_b32_e32 v111, 16, v66
	v_and_b32_e32 v109, 0xffff0000, v66
	v_lshlrev_b32_e32 v106, 16, v67
	v_and_b32_e32 v107, 0xffff0000, v67
	v_lshlrev_b32_e32 v66, 16, v68
	v_and_b32_e32 v67, 0xffff0000, v68
	v_lshlrev_b32_e32 v68, 16, v69
	v_and_b32_e32 v69, 0xffff0000, v69
	v_and_b32_e32 v103, 0xffff0000, v78
	v_mul_f32_e32 v78, v69, v69
	v_mul_f32_e32 v72, v67, v67
	v_lshlrev_b32_e32 v100, 16, v79
	v_and_b32_e32 v101, 0xffff0000, v79
	v_pk_fma_f32 v[78:79], v[68:69], v[68:69], v[78:79] op_sel_hi:[1,1,0]
	v_pk_fma_f32 v[72:73], v[66:67], v[66:67], v[72:73] op_sel_hi:[1,1,0]
	v_mov_b32_e32 v120, v78
	v_mov_b32_e32 v92, v72
	v_pk_add_f32 v[72:73], v[72:73], v[78:79]
	v_pk_mul_f32 v[78:79], v[92:93], v[120:121]
	v_lshlrev_b32_e32 v120, 16, v80
	v_mov_b32_e32 v73, v79
	v_pk_add_f32 v[70:71], v[72:73], v[70:71]
	v_mul_f32_e32 v72, v113, v113
	v_mul_f32_e32 v78, v115, v115
	v_pk_fma_f32 v[72:73], v[112:113], v[112:113], v[72:73] op_sel_hi:[1,1,0]
	v_pk_fma_f32 v[78:79], v[114:115], v[114:115], v[78:79] op_sel_hi:[1,1,0]
	v_mov_b32_e32 v73, v96
	v_mov_b32_e32 v79, v98
	v_pk_add_f32 v[72:73], v[72:73], v[78:79]
	v_and_b32_e32 v121, 0xffff0000, v80
	v_pk_add_f32 v[78:79], v[70:71], v[72:73]
	v_and_b32_e32 v71, 0xffff0000, v74
	v_and_b32_e32 v73, 0xffff0000, v75
	v_lshlrev_b32_e32 v70, 16, v74
	v_lshlrev_b32_e32 v72, 16, v75
	v_mul_f32_e32 v74, v73, v73
	v_mul_f32_e32 v80, v71, v71
	v_pk_fma_f32 v[74:75], v[72:73], v[72:73], v[74:75] op_sel_hi:[1,1,0]
	v_pk_fma_f32 v[80:81], v[70:71], v[70:71], v[80:81] op_sel_hi:[1,1,0]
	v_mov_b32_e32 v128, v74
	v_mov_b32_e32 v98, v80
	v_pk_add_f32 v[74:75], v[80:81], v[74:75]
	v_pk_mul_f32 v[80:81], v[98:99], v[128:129]
	v_mul_f32_e32 v92, v94, v94
	v_mov_b32_e32 v75, v81
	v_pk_add_f32 v[74:75], v[74:75], v[76:77]
	v_mul_f32_e32 v76, v121, v121
	v_mul_f32_e32 v80, v123, v123
	v_mul_f32_e32 v96, v95, v95
	v_pk_fma_f32 v[76:77], v[120:121], v[120:121], v[76:77] op_sel_hi:[1,1,0]
	v_pk_fma_f32 v[80:81], v[122:123], v[122:123], v[80:81] op_sel_hi:[1,1,0]
	v_mov_b32_e32 v77, v92
	v_mov_b32_e32 v81, v96
	v_pk_add_f32 v[76:77], v[76:77], v[80:81]
	v_lshlrev_b32_e32 v140, 16, v82
	v_pk_add_f32 v[80:81], v[74:75], v[76:77]
	v_lshlrev_b32_e32 v142, 16, v83
	v_mul_f32_e32 v74, v143, v143
	v_and_b32_e32 v135, 0xffff0000, v85
	v_and_b32_e32 v134, 0xffff0000, v84
	v_mul_f32_e32 v82, v141, v141
	v_pk_fma_f32 v[74:75], v[142:143], v[142:143], v[74:75] op_sel_hi:[1,1,0]
	v_lshlrev_b32_e32 v133, 16, v85
	v_lshlrev_b32_e32 v132, 16, v84
	v_pk_mul_f32 v[76:77], v[134:135], v[134:135]
	v_pk_fma_f32 v[82:83], v[140:141], v[140:141], v[82:83] op_sel_hi:[1,1,0]
	v_pk_fma_f32 v[76:77], v[132:133], v[132:133], v[76:77]
	v_mov_b32_e32 v104, v82
	v_mov_b32_e32 v84, v74
	v_mov_b32_e32 v85, v105
	v_mul_f32_e32 v90, v103, v103
	v_pk_add_f32 v[74:75], v[82:83], v[74:75]
	v_pk_mul_f32 v[82:83], v[104:105], v[84:85]
	v_pk_add_f32 v[76:77], v[76:77], v[76:77] op_sel:[0,1] op_sel_hi:[1,0]
	v_lshlrev_b32_e32 v128, 16, v130
	v_and_b32_e32 v129, 0xffff0000, v130
	v_lshlrev_b32_e32 v130, 16, v131
	v_and_b32_e32 v131, 0xffff0000, v131
	v_mov_b32_e32 v75, v83
	v_mov_b32_e32 v77, v90
	v_pk_add_f32 v[74:75], v[74:75], v[76:77]
	v_mul_f32_e32 v76, v129, v129
	v_mul_f32_e32 v82, v131, v131
	v_mul_f32_e32 v92, v100, v100
	v_mul_f32_e32 v96, v101, v101
	v_pk_fma_f32 v[76:77], v[128:129], v[128:129], v[76:77] op_sel_hi:[1,1,0]
	v_pk_fma_f32 v[82:83], v[130:131], v[130:131], v[82:83] op_sel_hi:[1,1,0]
	v_mov_b32_e32 v77, v92
	v_mov_b32_e32 v83, v96
	v_pk_add_f32 v[76:77], v[76:77], v[82:83]
	v_and_b32_e32 v149, 0xffff0000, v136
	v_and_b32_e32 v151, 0xffff0000, v137
	v_pk_add_f32 v[74:75], v[74:75], v[76:77]
	v_lshlrev_b32_e32 v148, 16, v136
	v_lshlrev_b32_e32 v150, 16, v137
	v_mul_f32_e32 v76, v151, v151
	v_and_b32_e32 v147, 0xffff0000, v139
	v_and_b32_e32 v146, 0xffff0000, v138
	v_mul_f32_e32 v84, v149, v149
	v_pk_fma_f32 v[76:77], v[150:151], v[150:151], v[76:77] op_sel_hi:[1,1,0]
	v_lshlrev_b32_e32 v145, 16, v139
	v_lshlrev_b32_e32 v144, 16, v138
	v_pk_mul_f32 v[82:83], v[146:147], v[146:147]
	v_pk_fma_f32 v[84:85], v[148:149], v[148:149], v[84:85] op_sel_hi:[1,1,0]
	v_pk_fma_f32 v[82:83], v[144:145], v[144:145], v[82:83]
	v_lshlrev_b32_e32 v136, 16, v152
	v_and_b32_e32 v137, 0xffff0000, v152
	v_lshlrev_b32_e32 v138, 16, v153
	v_and_b32_e32 v139, 0xffff0000, v153
	v_mov_b32_e32 v110, v84
	v_mov_b32_e32 v152, v76
	v_mov_b32_e32 v153, v111
	v_mul_f32_e32 v90, v109, v109
	v_pk_add_f32 v[76:77], v[84:85], v[76:77]
	v_pk_mul_f32 v[84:85], v[110:111], v[152:153]
	v_pk_add_f32 v[82:83], v[82:83], v[82:83] op_sel:[0,1] op_sel_hi:[1,0]
	v_mov_b32_e32 v77, v85
	v_mov_b32_e32 v83, v90
	v_pk_add_f32 v[76:77], v[76:77], v[82:83]
	v_mul_f32_e32 v82, v137, v137
	v_mul_f32_e32 v84, v139, v139
	v_mul_f32_e32 v92, v106, v106
	v_mul_f32_e32 v96, v107, v107
	v_pk_fma_f32 v[82:83], v[136:137], v[136:137], v[82:83] op_sel_hi:[1,1,0]
	v_pk_fma_f32 v[84:85], v[138:139], v[138:139], v[84:85] op_sel_hi:[1,1,0]
	v_mov_b32_e32 v83, v92
	v_mov_b32_e32 v85, v96
	v_pk_add_f32 v[82:83], v[82:83], v[84:85]
	v_mov_b64_e32 v[152:153], s[48:49]
	v_pk_add_f32 v[76:77], v[76:77], v[82:83]
	v_and_b32_e32 v82, 64, v232
	v_add_u32_e32 v82, 64, v82
	v_xor_b32_e32 v83, 1, v232
	v_cmp_lt_i32_e32 vcc, v83, v82
	v_mov_b32_e32 v90, v93
	v_mov_b32_e32 v102, v105
	v_cndmask_b32_e32 v83, v232, v83, vcc
	v_lshlrev_b32_e32 v92, 2, v83
	v_xor_b32_e32 v83, 2, v232
	v_cmp_lt_i32_e32 vcc, v83, v82
	v_mov_b32_e32 v108, v111
	s_nop 0
	v_cndmask_b32_e32 v83, v232, v83, vcc
	v_lshlrev_b32_e32 v162, 2, v83
	v_xor_b32_e32 v83, 4, v232
	v_cmp_lt_i32_e32 vcc, v83, v82
	s_nop 1
	v_cndmask_b32_e32 v83, v232, v83, vcc
	v_lshlrev_b32_e32 v163, 2, v83
	v_xor_b32_e32 v83, 8, v232
	v_cmp_lt_i32_e32 vcc, v83, v82
	s_nop 1
	v_cndmask_b32_e32 v83, v232, v83, vcc
	v_lshlrev_b32_e32 v164, 2, v83
	v_xor_b32_e32 v83, 16, v232
	v_cmp_lt_i32_e32 vcc, v83, v82
	s_nop 1
	v_cndmask_b32_e32 v83, v232, v83, vcc
	v_lshlrev_b32_e32 v165, 2, v83
	v_xor_b32_e32 v83, 32, v232
	v_cmp_lt_i32_e32 vcc, v83, v82
	s_nop 1
	v_cndmask_b32_e32 v82, v232, v83, vcc
	v_lshlrev_b32_e32 v166, 2, v82
	v_mov_b32_e32 v82, v80
	v_mov_b32_e32 v83, v78
	v_mov_b32_e32 v78, v81
	v_pk_add_f32 v[78:79], v[82:83], v[78:79]
	ds_bpermute_b32 v81, v92, v79
	ds_bpermute_b32 v80, v92, v78
	s_waitcnt lgkmcnt(0)
; __device__ __forceinline__ float wave_sum(float v) {
; #pragma unroll
;     for (int o = 1; o < 64; o <<= 1) v += __shfl_xor(v, o);
;     return v;
;     ...
;         for (int r = 0; r < NR; ++r) rr[r] = rsqrtf(wave_sum(rr[r]) * (1.f / 1024.f) + EPSN);
; #pragma unroll
;         for (int j = 0; j < 4; ++j) { const f32x4 g = *(const f32x4*)(gate + j * 256 + lane * 4) * *(const f32x4*)(gupd + j * 256 + lane * 4);
; #pragma unroll
;             for (int r = 0; r < NR; ++r) x[r][j] = x[r][j] + g * (y[r][j] * rr[r]); }
	v_pk_add_f32 v[78:79], v[78:79], v[80:81]
	ds_bpermute_b32 v81, v162, v79
	ds_bpermute_b32 v80, v162, v78
	s_waitcnt lgkmcnt(0)
	v_pk_add_f32 v[78:79], v[78:79], v[80:81]
	ds_bpermute_b32 v81, v163, v79
	ds_bpermute_b32 v80, v163, v78
	s_waitcnt lgkmcnt(0)
	v_pk_add_f32 v[78:79], v[78:79], v[80:81]
	ds_bpermute_b32 v81, v164, v79
	ds_bpermute_b32 v80, v164, v78
	s_waitcnt lgkmcnt(0)
	v_pk_add_f32 v[78:79], v[78:79], v[80:81]
	ds_bpermute_b32 v81, v165, v79
	ds_bpermute_b32 v80, v165, v78
	s_waitcnt lgkmcnt(0)
	v_pk_add_f32 v[78:79], v[78:79], v[80:81]
	ds_bpermute_b32 v81, v166, v79
	ds_bpermute_b32 v80, v166, v78
	s_waitcnt lgkmcnt(0)
	v_pk_add_f32 v[78:79], v[78:79], v[80:81]
	s_nop 0
	v_pk_fma_f32 v[78:79], v[78:79], s[72:73], v[152:153] op_sel_hi:[1,0,0]
	s_nop 0
	v_mul_f32_e32 v80, 0x4b800000, v79
	v_cmp_gt_f32_e64 s[12:13], s29, v79
	v_cmp_gt_f32_e32 vcc, s29, v78
	s_nop 0
	v_cndmask_b32_e64 v79, v79, v80, s[12:13]
	v_rsq_f32_e32 v79, v79
	s_nop 0
	v_mul_f32_e32 v80, 0x45800000, v79
	v_cndmask_b32_e64 v96, v79, v80, s[12:13]
	v_mul_f32_e32 v79, 0x4b800000, v78
	v_cndmask_b32_e32 v78, v78, v79, vcc
	v_rsq_f32_e32 v78, v78
	v_lshl_add_u64 v[80:81], s[40:41], 0, v[86:87]
	v_pk_mul_f32 v[68:69], v[96:97], v[68:69] op_sel_hi:[0,1]
	v_pk_mul_f32 v[66:67], v[96:97], v[66:67] op_sel_hi:[0,1]
	v_mul_f32_e32 v79, 0x45800000, v78
	v_cndmask_b32_e32 v98, v78, v79, vcc
	v_mov_b32_e32 v78, v76
	v_mov_b32_e32 v79, v74
	v_mov_b32_e32 v74, v77
	v_pk_add_f32 v[74:75], v[78:79], v[74:75]
	ds_bpermute_b32 v77, v92, v75
	ds_bpermute_b32 v76, v92, v74
	v_lshl_add_u64 v[154:155], v[80:81], 0, s[18:19]
	s_waitcnt lgkmcnt(0)
	v_pk_add_f32 v[74:75], v[74:75], v[76:77]
	ds_bpermute_b32 v77, v162, v75
	ds_bpermute_b32 v76, v162, v74
	s_waitcnt lgkmcnt(0)
	v_pk_add_f32 v[74:75], v[74:75], v[76:77]
	ds_bpermute_b32 v77, v163, v75
	ds_bpermute_b32 v76, v163, v74
	s_waitcnt lgkmcnt(0)
	v_pk_add_f32 v[74:75], v[74:75], v[76:77]
	ds_bpermute_b32 v77, v164, v75
	ds_bpermute_b32 v76, v164, v74
	s_waitcnt lgkmcnt(0)
	v_pk_add_f32 v[74:75], v[74:75], v[76:77]
	ds_bpermute_b32 v77, v165, v75
	ds_bpermute_b32 v76, v165, v74
	s_waitcnt lgkmcnt(0)
	v_pk_add_f32 v[74:75], v[74:75], v[76:77]
	ds_bpermute_b32 v77, v166, v75
	ds_bpermute_b32 v76, v166, v74
	s_waitcnt lgkmcnt(0)
	v_pk_add_f32 v[74:75], v[74:75], v[76:77]
	s_nop 0
	v_pk_fma_f32 v[74:75], v[74:75], s[72:73], v[152:153] op_sel_hi:[1,0,0]
	s_nop 0
	v_mul_f32_e32 v76, 0x4b800000, v75
	v_cmp_gt_f32_e64 s[12:13], s29, v75
	v_cmp_gt_f32_e32 vcc, s29, v74
	s_nop 0
	v_cndmask_b32_e64 v75, v75, v76, s[12:13]
	v_rsq_f32_e32 v75, v75
	s_nop 0
	v_mul_f32_e32 v76, 0x45800000, v75
	v_cndmask_b32_e64 v104, v75, v76, s[12:13]
	v_mul_f32_e32 v75, 0x4b800000, v74
	v_cndmask_b32_e32 v74, v74, v75, vcc
	v_rsq_f32_e32 v74, v74
	s_nop 0
	v_mul_f32_e32 v75, 0x45800000, v74
	v_cndmask_b32_e32 v110, v74, v75, vcc
	v_add_co_u32_e32 v78, vcc, s38, v80
	s_nop 1
	v_addc_co_u32_e32 v79, vcc, 0, v81, vcc
	global_load_dwordx4 v[74:77], v[78:79], off offset:-4096
	global_load_dwordx4 v[82:85], v[156:157], off
	s_waitcnt vmcnt(0)
	v_pk_mul_f32 v[158:159], v[76:77], v[84:85]
	v_pk_mul_f32 v[160:161], v[74:75], v[82:83]
	v_pk_fma_f32 v[84:85], v[68:69], v[158:159], v[50:51]
	v_pk_fma_f32 v[82:83], v[66:67], v[160:161], v[48:49]
	v_pk_mul_f32 v[48:49], v[98:99], v[72:73] op_sel_hi:[0,1]
	v_pk_mul_f32 v[50:51], v[98:99], v[70:71] op_sel_hi:[0,1]
	v_pk_fma_f32 v[74:75], v[50:51], v[160:161], v[52:53]
	v_pk_fma_f32 v[76:77], v[48:49], v[158:159], v[54:55]
	v_pk_mul_f32 v[48:49], v[104:105], v[142:143] op_sel_hi:[0,1]
	v_pk_mul_f32 v[50:51], v[104:105], v[140:141] op_sel_hi:[0,1]
	v_pk_fma_f32 v[70:71], v[160:161], v[50:51], v[56:57]
	v_pk_fma_f32 v[72:73], v[158:159], v[48:49], v[58:59]
	v_pk_mul_f32 v[48:49], v[110:111], v[150:151] op_sel_hi:[0,1]
	v_pk_mul_f32 v[50:51], v[110:111], v[148:149] op_sel_hi:[0,1]
	v_pk_fma_f32 v[66:67], v[160:161], v[50:51], v[60:61]
	v_pk_fma_f32 v[68:69], v[158:159], v[48:49], v[62:63]
	global_load_dwordx4 v[48:51], v[154:155], off offset:1024
	global_load_dwordx4 v[52:55], v[156:157], off offset:1024
	s_waitcnt vmcnt(0)
	v_pk_mul_f32 v[60:61], v[48:49], v[52:53]
	v_mov_b32_e32 v48, v117
	v_mov_b32_e32 v117, v118
	v_pk_mul_f32 v[58:59], v[50:51], v[54:55]
	v_pk_mul_f32 v[50:51], v[96:97], v[116:117] op_sel_hi:[0,1]
	v_mov_b32_e32 v49, v119
	v_pk_fma_f32 v[54:55], v[50:51], v[60:61], v[40:41]
	v_mov_b32_e32 v40, v125
	v_mov_b32_e32 v41, v127
	v_pk_mul_f32 v[48:49], v[96:97], v[48:49] op_sel_hi:[0,1]
	v_pk_mul_f32 v[40:41], v[98:99], v[40:41] op_sel_hi:[0,1]
	v_mov_b32_e32 v125, v126
	v_pk_fma_f32 v[56:57], v[48:49], v[58:59], v[42:43]
	v_pk_mul_f32 v[42:43], v[98:99], v[124:125] op_sel_hi:[0,1]
	v_pk_fma_f32 v[52:53], v[40:41], v[58:59], v[46:47]
	v_mov_b32_e32 v40, v133
	v_mov_b32_e32 v133, v134
	v_pk_fma_f32 v[50:51], v[42:43], v[60:61], v[44:45]
	v_mov_b32_e32 v41, v135
	v_pk_mul_f32 v[42:43], v[104:105], v[132:133] op_sel_hi:[0,1]
	v_pk_mul_f32 v[40:41], v[104:105], v[40:41] op_sel_hi:[0,1]
	v_pk_fma_f32 v[46:47], v[60:61], v[42:43], v[36:37]
	v_mov_b32_e32 v36, v145
	v_mov_b32_e32 v37, v147
	v_mov_b32_e32 v145, v146
	v_pk_fma_f32 v[48:49], v[58:59], v[40:41], v[38:39]
	v_pk_mul_f32 v[36:37], v[110:111], v[36:37] op_sel_hi:[0,1]
	v_pk_mul_f32 v[38:39], v[110:111], v[144:145] op_sel_hi:[0,1]
	v_pk_fma_f32 v[42:43], v[60:61], v[38:39], v[32:33]
	v_pk_fma_f32 v[44:45], v[58:59], v[36:37], v[34:35]
	global_load_dwordx4 v[32:35], v[154:155], off offset:2048
	global_load_dwordx4 v[36:39], v[156:157], off offset:2048
	s_waitcnt vmcnt(0)
;     ...
;         for (int r = 0; r < NR; ++r) { float ss = 0.f;
; #pragma unroll
;             for (int j = 0; j < 4; ++j) ss += (y[r][j][0] * y[r][j][0] + y[r][j][1] * y[r][j][1]) + (y[r][j][2] * y[r][j][2] + y[r][j][3] * y[r][j][3]);
;             rr[r] = ss; }
; #pragma unroll
;         for (int r = 0; r < NR; ++r) rr[r] = rsqrtf(wave_sum(rr[r]) * (1.f / 1024.f) + EPSN);
; #pragma unroll
;         for (int j = 0; j < 4; ++j) { const f32x4 g = *(const f32x4*)(gate + j * 256 + lane * 4) * *(const f32x4*)(gupd + j * 256 + lane * 4);
; #pragma unroll
;             for (int r = 0; r < NR; ++r) x[r][j] = x[r][j] + g * (y[r][j] * rr[r]); }
;     ...
;     if (hxout) {
;         float rr[NR];
; #pragma unroll
;         for (int r = 0; r < NR; ++r) { float ss = 0.f;
; #pragma unroll
;             for (int j = 0; j < 4; ++j) ss += (x[r][j][0] * x[r][j][0] + x[r][j][1] * x[r][j][1]) + (x[r][j][2] * x[r][j][2] + x[r][j][3] * x[r][j][3]);
;             rr[r] = ss; }
	v_pk_mul_f32 v[40:41], v[34:35], v[38:39]
	v_pk_mul_f32 v[58:59], v[32:33], v[36:37]
	v_pk_mul_f32 v[32:33], v[96:97], v[112:113] op_sel_hi:[0,1]
	v_pk_mul_f32 v[34:35], v[96:97], v[114:115] op_sel_hi:[0,1]
	v_pk_fma_f32 v[36:37], v[34:35], v[40:41], v[18:19]
	v_pk_fma_f32 v[38:39], v[32:33], v[58:59], v[16:17]
	v_pk_mul_f32 v[16:17], v[98:99], v[120:121] op_sel_hi:[0,1]
	v_pk_mul_f32 v[18:19], v[98:99], v[122:123] op_sel_hi:[0,1]
	v_pk_fma_f32 v[32:33], v[18:19], v[40:41], v[22:23]
	v_pk_fma_f32 v[34:35], v[16:17], v[58:59], v[20:21]
	v_pk_mul_f32 v[16:17], v[104:105], v[128:129] op_sel_hi:[0,1]
	v_pk_mul_f32 v[18:19], v[104:105], v[130:131] op_sel_hi:[0,1]
	v_pk_fma_f32 v[26:27], v[18:19], v[40:41], v[26:27]
	v_pk_fma_f32 v[24:25], v[16:17], v[58:59], v[24:25]
	v_pk_mul_f32 v[16:17], v[110:111], v[136:137] op_sel_hi:[0,1]
	v_pk_mul_f32 v[18:19], v[110:111], v[138:139] op_sel_hi:[0,1]
	v_pk_fma_f32 v[20:21], v[40:41], v[18:19], v[30:31]
	v_pk_fma_f32 v[22:23], v[58:59], v[16:17], v[28:29]
	global_load_dwordx4 v[16:19], v[154:155], off offset:3072
	global_load_dwordx4 v[28:31], v[156:157], off offset:3072
	s_waitcnt vmcnt(0)
	v_pk_mul_f32 v[30:31], v[18:19], v[30:31]
	v_pk_mul_f32 v[28:29], v[16:17], v[28:29]
	v_pk_mul_f32 v[18:19], v[96:97], v[90:91] op_sel_hi:[0,1]
	v_pk_mul_f32 v[16:17], v[96:97], v[88:89] op_sel_hi:[0,1]
	v_mov_b32_e32 v96, v99
	v_pk_fma_f32 v[16:17], v[16:17], v[30:31], v[2:3]
	v_pk_fma_f32 v[18:19], v[18:19], v[28:29], v[0:1]
	v_pk_mul_f32 v[0:1], v[98:99], v[96:97] op_sel_hi:[0,1]
	v_pk_mul_f32 v[2:3], v[98:99], v[94:95] op_sel_hi:[0,1]
	v_pk_fma_f32 v[10:11], v[2:3], v[30:31], v[10:11]
	v_pk_fma_f32 v[8:9], v[0:1], v[28:29], v[8:9]
	v_pk_mul_f32 v[0:1], v[104:105], v[102:103] op_sel_hi:[0,1]
	v_pk_mul_f32 v[2:3], v[104:105], v[100:101] op_sel_hi:[0,1]
	v_pk_fma_f32 v[2:3], v[2:3], v[30:31], v[6:7]
	v_pk_fma_f32 v[6:7], v[0:1], v[28:29], v[4:5]
	v_pk_mul_f32 v[4:5], v[110:111], v[108:109] op_sel_hi:[0,1]
	v_pk_mul_f32 v[0:1], v[110:111], v[106:107] op_sel_hi:[0,1]
	v_pk_fma_f32 v[0:1], v[30:31], v[0:1], v[14:15]
	v_pk_fma_f32 v[4:5], v[28:29], v[4:5], v[12:13]
	v_pk_mul_f32 v[12:13], v[84:85], v[84:85]
	v_pk_mul_f32 v[14:15], v[82:83], v[82:83]
	s_nop 0
	v_pk_mov_b32 v[28:29], v[14:15], v[12:13] op_sel:[1,0]
	v_mov_b32_e32 v15, v13
	v_pk_add_f32 v[12:13], v[28:29], v[14:15]
	v_pk_mul_f32 v[14:15], v[56:57], v[56:57]
	v_pk_mul_f32 v[28:29], v[54:55], v[54:55]
	v_pk_add_f32 v[12:13], v[12:13], v[12:13] op_sel:[0,1] op_sel_hi:[1,0]
	v_pk_mov_b32 v[30:31], v[28:29], v[14:15] op_sel:[1,0]
	v_mov_b32_e32 v29, v15
	v_pk_add_f32 v[14:15], v[30:31], v[28:29]
	v_mul_f32_e32 v28, v18, v18
	v_mul_f32_e32 v29, v19, v19
	v_pk_add_f32 v[14:15], v[14:15], v[14:15] op_sel:[0,1] op_sel_hi:[1,0]
	v_mov_b32_e32 v13, v28
	v_mov_b32_e32 v15, v29
	v_pk_add_f32 v[12:13], v[12:13], v[14:15]
	v_mul_f32_e32 v14, v39, v39
	v_mul_f32_e32 v28, v37, v37
	v_mul_f32_e32 v30, v16, v16
	v_mul_f32_e32 v31, v17, v17
	v_pk_fma_f32 v[14:15], v[38:39], v[38:39], v[14:15] op_sel_hi:[1,1,0]
	v_pk_fma_f32 v[28:29], v[36:37], v[36:37], v[28:29] op_sel_hi:[1,1,0]
	v_mov_b32_e32 v15, v30
	v_mov_b32_e32 v29, v31
	v_pk_add_f32 v[14:15], v[14:15], v[28:29]
	v_pk_mul_f32 v[28:29], v[74:75], v[74:75]
	v_pk_add_f32 v[12:13], v[12:13], v[14:15]
	v_pk_mul_f32 v[14:15], v[76:77], v[76:77]
	s_nop 0
	v_pk_mov_b32 v[30:31], v[28:29], v[14:15] op_sel:[1,0]
	v_mov_b32_e32 v29, v15
	v_pk_add_f32 v[14:15], v[30:31], v[28:29]
	v_pk_mul_f32 v[28:29], v[52:53], v[52:53]
	v_pk_mul_f32 v[30:31], v[50:51], v[50:51]
	v_pk_add_f32 v[14:15], v[14:15], v[14:15] op_sel:[0,1] op_sel_hi:[1,0]
	v_pk_mov_b32 v[40:41], v[30:31], v[28:29] op_sel:[1,0]
	v_mov_b32_e32 v31, v29
	v_pk_add_f32 v[28:29], v[40:41], v[30:31]
	v_mul_f32_e32 v30, v8, v8
	v_mul_f32_e32 v31, v9, v9
	v_pk_add_f32 v[28:29], v[28:29], v[28:29] op_sel:[0,1] op_sel_hi:[1,0]
	v_mov_b32_e32 v15, v30
	v_mov_b32_e32 v29, v31
	v_pk_add_f32 v[14:15], v[14:15], v[28:29]
	v_mul_f32_e32 v28, v35, v35
	v_mul_f32_e32 v30, v33, v33
	v_mul_f32_e32 v40, v10, v10
	v_mul_f32_e32 v41, v11, v11
	v_pk_fma_f32 v[28:29], v[34:35], v[34:35], v[28:29] op_sel_hi:[1,1,0]
	v_pk_fma_f32 v[30:31], v[32:33], v[32:33], v[30:31] op_sel_hi:[1,1,0]
	v_mov_b32_e32 v29, v40
	v_mov_b32_e32 v31, v41
	v_pk_add_f32 v[28:29], v[28:29], v[30:31]
	v_pk_mul_f32 v[30:31], v[70:71], v[70:71]
	v_pk_add_f32 v[14:15], v[14:15], v[28:29]
	v_pk_mul_f32 v[28:29], v[72:73], v[72:73]
	s_nop 0
	v_pk_mov_b32 v[40:41], v[30:31], v[28:29] op_sel:[1,0]
	v_mov_b32_e32 v31, v29
	v_pk_add_f32 v[28:29], v[40:41], v[30:31]
	v_pk_mul_f32 v[30:31], v[48:49], v[48:49]
	v_pk_mul_f32 v[40:41], v[46:47], v[46:47]
	v_pk_add_f32 v[28:29], v[28:29], v[28:29] op_sel:[0,1] op_sel_hi:[1,0]
	v_pk_mov_b32 v[58:59], v[40:41], v[30:31] op_sel:[1,0]
	v_mov_b32_e32 v41, v31
	v_pk_add_f32 v[30:31], v[58:59], v[40:41]
	v_mul_f32_e32 v40, v6, v6
	v_mul_f32_e32 v41, v7, v7
	v_pk_add_f32 v[30:31], v[30:31], v[30:31] op_sel:[0,1] op_sel_hi:[1,0]
	v_mov_b32_e32 v29, v40
	v_mov_b32_e32 v31, v41
	v_pk_add_f32 v[28:29], v[28:29], v[30:31]
	v_mul_f32_e32 v30, v25, v25
	v_mul_f32_e32 v40, v27, v27
	v_mul_f32_e32 v58, v2, v2
	v_mul_f32_e32 v59, v3, v3
	v_pk_fma_f32 v[30:31], v[24:25], v[24:25], v[30:31] op_sel_hi:[1,1,0]
	v_pk_fma_f32 v[40:41], v[26:27], v[26:27], v[40:41] op_sel_hi:[1,1,0]
	v_mov_b32_e32 v31, v58
	v_mov_b32_e32 v41, v59
	v_pk_add_f32 v[30:31], v[30:31], v[40:41]
	v_pk_mul_f32 v[40:41], v[66:67], v[66:67]
	v_pk_add_f32 v[28:29], v[28:29], v[30:31]
	v_pk_mul_f32 v[30:31], v[68:69], v[68:69]
	s_nop 0
	v_pk_mov_b32 v[58:59], v[40:41], v[30:31] op_sel:[1,0]
	v_mov_b32_e32 v41, v31
	v_pk_add_f32 v[30:31], v[58:59], v[40:41]
	v_pk_mul_f32 v[40:41], v[44:45], v[44:45]
	v_pk_mul_f32 v[58:59], v[42:43], v[42:43]
	v_pk_add_f32 v[30:31], v[30:31], v[30:31] op_sel_hi:[0,1]
	v_pk_mov_b32 v[60:61], v[58:59], v[40:41] op_sel:[1,0]
	v_mov_b32_e32 v59, v41
	v_pk_add_f32 v[40:41], v[60:61], v[58:59]
	v_mul_f32_e32 v30, v22, v22
	v_pk_add_f32 v[40:41], v[40:41], v[40:41] op_sel_hi:[0,1]
	v_pk_fma_f32 v[58:59], v[22:23], v[22:23], v[30:31] op_sel_hi:[1,1,0]
	v_mul_f32_e32 v30, v20, v20
	v_pk_fma_f32 v[60:61], v[20:21], v[20:21], v[30:31] op_sel_hi:[1,1,0]
	v_mul_f32_e32 v30, v0, v0
	v_mul_f32_e32 v40, v1, v1
	v_pk_add_f32 v[30:31], v[30:31], v[40:41]
	v_mov_b32_e32 v40, v14
	v_mov_b32_e32 v41, v12
	v_mov_b32_e32 v12, v15
	v_pk_add_f32 v[12:13], v[40:41], v[12:13]
	ds_bpermute_b32 v15, v92, v13
	ds_bpermute_b32 v14, v92, v12
	v_mul_f32_e32 v58, v4, v4
	v_mul_f32_e32 v60, v5, v5
	v_pk_add_f32 v[58:59], v[58:59], v[60:61]
	v_mov_b32_e32 v41, v28
	s_waitcnt lgkmcnt(0)
;     ...
; #pragma unroll
;         for (int r = 0; r < NR; ++r) rr[r] = rsqrtf(wave_sum(rr[r]) * (1.f / 1024.f) + EPSN);
; #pragma unroll
;         for (int j = 0; j < 4; ++j) { const f32x4 g = *(const f32x4*)(gn + j * 256 + lane * 4) * (*(const f32x4*)(sc + j * 256 + lane * 4) + 1.f), s0 = *(const f32x4*)(sh + j * 256 + lane * 4);
; #pragma unroll
	v_pk_add_f32 v[12:13], v[12:13], v[14:15]
	ds_bpermute_b32 v15, v162, v13
	ds_bpermute_b32 v14, v162, v12
	v_pk_add_f32 v[30:31], v[58:59], v[30:31]
	v_lshl_add_u64 v[60:61], v[80:81], 0, s[6:7]
	v_mov_b32_e32 v40, v30
	v_mov_b32_e32 v28, v31
	s_waitcnt lgkmcnt(0)
	v_pk_add_f32 v[12:13], v[12:13], v[14:15]
	ds_bpermute_b32 v15, v163, v13
	ds_bpermute_b32 v14, v163, v12
	v_pk_add_f32 v[28:29], v[40:41], v[28:29]
	ds_bpermute_b32 v31, v92, v29
	ds_bpermute_b32 v30, v92, v28
	v_lshl_add_u64 v[40:41], s[26:27], 0, v[86:87]
	s_waitcnt lgkmcnt(2)
	v_pk_add_f32 v[12:13], v[12:13], v[14:15]
	ds_bpermute_b32 v15, v164, v13
	ds_bpermute_b32 v14, v164, v12
	s_waitcnt lgkmcnt(2)
	v_pk_add_f32 v[28:29], v[28:29], v[30:31]
	ds_bpermute_b32 v31, v162, v29
	ds_bpermute_b32 v30, v162, v28
	global_load_dwordx4 v[86:89], v[40:41], off
	s_waitcnt lgkmcnt(2)
	v_pk_add_f32 v[12:13], v[12:13], v[14:15]
	ds_bpermute_b32 v15, v165, v13
	ds_bpermute_b32 v14, v165, v12
	s_waitcnt lgkmcnt(2)
	v_pk_add_f32 v[28:29], v[28:29], v[30:31]
	ds_bpermute_b32 v31, v163, v29
	ds_bpermute_b32 v30, v163, v28
	s_mov_b64 s[6:7], 0x3000
	s_waitcnt lgkmcnt(2)
	v_pk_add_f32 v[12:13], v[12:13], v[14:15]
	ds_bpermute_b32 v15, v166, v13
	ds_bpermute_b32 v14, v166, v12
	s_waitcnt lgkmcnt(2)
	v_pk_add_f32 v[28:29], v[28:29], v[30:31]
	ds_bpermute_b32 v31, v164, v29
	ds_bpermute_b32 v30, v164, v28
	v_lshl_add_u64 v[58:59], v[80:81], 0, s[6:7]
	s_waitcnt lgkmcnt(2)
	v_pk_add_f32 v[12:13], v[12:13], v[14:15]
	s_waitcnt lgkmcnt(0)
	v_pk_add_f32 v[28:29], v[28:29], v[30:31]
	v_pk_fma_f32 v[12:13], v[12:13], s[72:73], v[152:153] op_sel_hi:[1,0,0]
	ds_bpermute_b32 v31, v165, v29
	v_mul_f32_e32 v14, 0x4b800000, v13
	v_cmp_gt_f32_e64 s[12:13], s29, v13
	ds_bpermute_b32 v30, v165, v28
	v_cmp_gt_f32_e32 vcc, s29, v12
	v_cndmask_b32_e64 v13, v13, v14, s[12:13]
	v_rsq_f32_e32 v13, v13
	s_waitcnt lgkmcnt(0)
	v_pk_add_f32 v[28:29], v[28:29], v[30:31]
	ds_bpermute_b32 v31, v166, v29
	v_mul_f32_e32 v14, 0x45800000, v13
	v_cndmask_b32_e64 v14, v13, v14, s[12:13]
	v_mul_f32_e32 v13, 0x4b800000, v12
	ds_bpermute_b32 v30, v166, v28
	v_cndmask_b32_e32 v12, v12, v13, vcc
	v_rsq_f32_e32 v12, v12
	s_waitcnt lgkmcnt(0)
	v_pk_add_f32 v[28:29], v[28:29], v[30:31]
	v_mul_f32_e32 v13, 0x45800000, v12
	v_pk_fma_f32 v[28:29], v[28:29], s[72:73], v[152:153] op_sel_hi:[1,0,0]
	v_cndmask_b32_e32 v12, v12, v13, vcc
	v_mul_f32_e32 v13, 0x4b800000, v29
	v_cmp_gt_f32_e64 s[12:13], s29, v29
	v_cmp_gt_f32_e32 vcc, s29, v28
	s_nop 0
	v_cndmask_b32_e64 v13, v29, v13, s[12:13]
	v_rsq_f32_e32 v13, v13
	s_nop 0
	v_mul_f32_e32 v15, 0x45800000, v13
	v_cndmask_b32_e64 v30, v13, v15, s[12:13]
	v_mul_f32_e32 v13, 0x4b800000, v28
	v_cndmask_b32_e32 v13, v28, v13, vcc
	v_rsq_f32_e32 v13, v13
	v_pk_mul_f32 v[70:71], v[70:71], v[30:31] op_sel_hi:[1,0]
	v_pk_mul_f32 v[72:73], v[72:73], v[30:31] op_sel_hi:[1,0]
	v_pk_mul_f32 v[46:47], v[46:47], v[30:31] op_sel_hi:[1,0]
	v_mul_f32_e32 v15, 0x45800000, v13
	v_cndmask_b32_e32 v28, v13, v15, vcc
	v_add_co_u32_e32 v62, vcc, s5, v80
	v_pk_mul_f32 v[74:75], v[74:75], v[12:13] op_sel_hi:[1,0]
	s_nop 0
	v_addc_co_u32_e32 v63, vcc, 0, v81, vcc
	global_load_dwordx4 v[90:93], v[62:63], off
	v_pk_mul_f32 v[66:67], v[66:67], v[28:29] op_sel_hi:[1,0]
	v_pk_mul_f32 v[76:77], v[76:77], v[12:13] op_sel_hi:[1,0]
	v_pk_mul_f32 v[68:69], v[68:69], v[28:29] op_sel_hi:[1,0]
	v_pk_mul_f32 v[54:55], v[54:55], v[14:15] op_sel_hi:[1,0]
	v_pk_mul_f32 v[50:51], v[50:51], v[12:13] op_sel_hi:[1,0]
	v_pk_mul_f32 v[42:43], v[42:43], v[28:29] op_sel_hi:[1,0]
	v_pk_mul_f32 v[56:57], v[56:57], v[14:15] op_sel_hi:[1,0]
	v_pk_mul_f32 v[52:53], v[52:53], v[12:13] op_sel_hi:[1,0]
	v_pk_mul_f32 v[48:49], v[48:49], v[30:31] op_sel_hi:[1,0]
	v_pk_mul_f32 v[44:45], v[44:45], v[28:29] op_sel_hi:[1,0]
	v_pk_mul_f32 v[38:39], v[38:39], v[14:15] op_sel_hi:[1,0]
	v_pk_mul_f32 v[34:35], v[34:35], v[12:13] op_sel_hi:[1,0]
	v_pk_mul_f32 v[24:25], v[24:25], v[30:31] op_sel_hi:[1,0]
	v_pk_mul_f32 v[22:23], v[22:23], v[28:29] op_sel_hi:[1,0]
	v_pk_mul_f32 v[36:37], v[36:37], v[14:15] op_sel_hi:[1,0]
	v_pk_mul_f32 v[32:33], v[32:33], v[12:13] op_sel_hi:[1,0]
	v_pk_mul_f32 v[26:27], v[26:27], v[30:31] op_sel_hi:[1,0]
	v_pk_mul_f32 v[20:21], v[20:21], v[28:29] op_sel_hi:[1,0]
	v_pk_mul_f32 v[18:19], v[18:19], v[14:15] op_sel_hi:[1,0]
	v_pk_mul_f32 v[8:9], v[8:9], v[12:13] op_sel_hi:[1,0]
	v_pk_mul_f32 v[6:7], v[6:7], v[30:31] op_sel_hi:[1,0]
	v_pk_mul_f32 v[2:3], v[2:3], v[30:31] op_sel_hi:[1,0]
	v_pk_mul_f32 v[10:11], v[10:11], v[12:13] op_sel_hi:[1,0]
	v_pk_mul_f32 v[0:1], v[0:1], v[28:29] op_sel_hi:[1,0]
	s_waitcnt vmcnt(0)
	v_pk_add_f32 v[80:81], v[90:91], 1.0 op_sel_hi:[1,0]
	s_nop 0
	v_pk_mul_f32 v[86:87], v[86:87], v[80:81]
	global_load_dwordx4 v[78:81], v[78:79], off
	v_pk_add_f32 v[62:63], v[92:93], 1.0 op_sel_hi:[1,0]
	s_waitcnt vmcnt(0)
; __device__ __forceinline__ unsigned cvt_pk_bf16(float lo, float hi) { unsigned r; asm volatile("v_cvt_pk_bf16_f32 %0, %1, %2" : "=v"(r) : "v"(lo), "v"(hi)); return r; }
;     ...
;         for (int j = 0; j < 4; ++j) { const f32x4 g = *(const f32x4*)(gn + j * 256 + lane * 4) * (*(const f32x4*)(sc + j * 256 + lane * 4) + 1.f), s0 = *(const f32x4*)(sh + j * 256 + lane * 4);
; #pragma unroll
;             for (int r = 0; r < NR; ++r) { const f32x4 h = (x[r][j] * rr[r]) * g + s0; v2u w; w.x = cvt_pk_bf16(h[0], h[1]); w.y = cvt_pk_bf16(h[2], h[3]); *(v2u*)(hxout + (size_t)r * DM + j * 256 + lane * 4) = w; } }
	v_pk_fma_f32 v[74:75], v[74:75], v[86:87], v[78:79]
	v_pk_mul_f32 v[88:89], v[88:89], v[62:63]
	v_pk_mul_f32 v[62:63], v[82:83], v[14:15] op_sel_hi:[1,0]
	v_pk_mul_f32 v[82:83], v[84:85], v[14:15] op_sel_hi:[1,0]
	v_pk_fma_f32 v[62:63], v[62:63], v[86:87], v[78:79]
	v_pk_fma_f32 v[70:71], v[86:87], v[70:71], v[78:79]
	v_cvt_pk_bf16_f32 v84, v62, v63
	v_add_co_u32_e32 v62, vcc, s39, v64
	v_pk_fma_f32 v[66:67], v[86:87], v[66:67], v[78:79]
	s_nop 0
	v_addc_co_u32_e32 v63, vcc, -1, v65, vcc
	v_add_co_u32_e32 v64, vcc, s46, v64
	v_pk_fma_f32 v[82:83], v[82:83], v[88:89], v[80:81]
	s_nop 0
	v_addc_co_u32_e32 v65, vcc, -1, v65, vcc
	v_cvt_pk_bf16_f32 v85, v82, v83
	global_store_dwordx2 v[62:63], v[84:85], off offset:-4096
	v_pk_fma_f32 v[76:77], v[76:77], v[88:89], v[80:81]
	v_cvt_pk_bf16_f32 v74, v74, v75
	v_pk_fma_f32 v[72:73], v[88:89], v[72:73], v[80:81]
	v_cvt_pk_bf16_f32 v75, v76, v77
	global_store_dwordx2 v[62:63], v[74:75], off offset:-2048
	v_cvt_pk_bf16_f32 v70, v70, v71
	v_cvt_pk_bf16_f32 v71, v72, v73
	global_store_dwordx2 v[62:63], v[70:71], off
	v_pk_fma_f32 v[68:69], v[88:89], v[68:69], v[80:81]
	v_cvt_pk_bf16_f32 v66, v66, v67
	v_pk_mul_f32 v[14:15], v[16:17], v[14:15] op_sel_hi:[1,0]
	v_cvt_pk_bf16_f32 v67, v68, v69
	global_store_dwordx2 v[64:65], v[66:67], off offset:-2048
	global_load_dwordx4 v[66:69], v[40:41], off offset:1024
	s_nop 0
	global_load_dwordx4 v[70:73], v[60:61], off offset:1024
	s_waitcnt vmcnt(0)
	v_pk_add_f32 v[72:73], v[72:73], 1.0 op_sel_hi:[1,0]
	v_pk_add_f32 v[70:71], v[70:71], 1.0 op_sel_hi:[1,0]
	v_pk_mul_f32 v[72:73], v[68:69], v[72:73]
	v_pk_mul_f32 v[70:71], v[66:67], v[70:71]
	global_load_dwordx4 v[66:69], v[58:59], off offset:1024
	s_waitcnt vmcnt(0)
	v_pk_fma_f32 v[54:55], v[54:55], v[70:71], v[66:67]
	v_pk_fma_f32 v[50:51], v[50:51], v[70:71], v[66:67]
	v_pk_fma_f32 v[46:47], v[46:47], v[70:71], v[66:67]
	v_pk_fma_f32 v[42:43], v[42:43], v[70:71], v[66:67]
	v_pk_fma_f32 v[56:57], v[56:57], v[72:73], v[68:69]
	v_cvt_pk_bf16_f32 v54, v54, v55
	v_pk_fma_f32 v[52:53], v[52:53], v[72:73], v[68:69]
	v_cvt_pk_bf16_f32 v55, v56, v57
	global_store_dwordx2 v[62:63], v[54:55], off offset:-3584
	v_cvt_pk_bf16_f32 v50, v50, v51
	v_cvt_pk_bf16_f32 v51, v52, v53
	global_store_dwordx2 v[62:63], v[50:51], off offset:-1536
	v_pk_fma_f32 v[48:49], v[48:49], v[72:73], v[68:69]
	v_cvt_pk_bf16_f32 v46, v46, v47
	v_pk_fma_f32 v[44:45], v[44:45], v[72:73], v[68:69]
	v_cvt_pk_bf16_f32 v47, v48, v49
	global_store_dwordx2 v[64:65], v[46:47], off offset:-3584
	v_cvt_pk_bf16_f32 v42, v42, v43
	v_cvt_pk_bf16_f32 v43, v44, v45
	global_store_dwordx2 v[64:65], v[42:43], off offset:-1536
	global_load_dwordx4 v[42:45], v[40:41], off offset:2048
	s_nop 0
	global_load_dwordx4 v[46:49], v[60:61], off offset:2048
	s_waitcnt vmcnt(0)
	v_pk_add_f32 v[48:49], v[48:49], 1.0 op_sel_hi:[1,0]
	v_pk_add_f32 v[46:47], v[46:47], 1.0 op_sel_hi:[1,0]
	v_pk_mul_f32 v[48:49], v[44:45], v[48:49]
	v_pk_mul_f32 v[46:47], v[42:43], v[46:47]
	global_load_dwordx4 v[42:45], v[58:59], off offset:2048
	s_waitcnt vmcnt(0)
	v_pk_fma_f32 v[38:39], v[38:39], v[46:47], v[42:43]
	v_pk_fma_f32 v[34:35], v[34:35], v[46:47], v[42:43]
	v_pk_fma_f32 v[24:25], v[24:25], v[46:47], v[42:43]
	v_pk_fma_f32 v[22:23], v[22:23], v[46:47], v[42:43]
	v_pk_fma_f32 v[36:37], v[36:37], v[48:49], v[44:45]
	v_cvt_pk_bf16_f32 v38, v38, v39
	v_pk_fma_f32 v[32:33], v[32:33], v[48:49], v[44:45]
	v_cvt_pk_bf16_f32 v39, v36, v37
	global_store_dwordx2 v[62:63], v[38:39], off offset:-3072
	v_cvt_pk_bf16_f32 v34, v34, v35
	v_cvt_pk_bf16_f32 v35, v32, v33
	global_store_dwordx2 v[62:63], v[34:35], off offset:-1024
	v_pk_fma_f32 v[26:27], v[26:27], v[48:49], v[44:45]
	v_cvt_pk_bf16_f32 v24, v24, v25
	v_pk_fma_f32 v[20:21], v[20:21], v[48:49], v[44:45]
	v_cvt_pk_bf16_f32 v25, v26, v27
	global_store_dwordx2 v[64:65], v[24:25], off offset:-3072
	v_cvt_pk_bf16_f32 v22, v22, v23
	v_cvt_pk_bf16_f32 v23, v20, v21
	global_store_dwordx2 v[64:65], v[22:23], off offset:-1024
	global_load_dwordx4 v[20:23], v[40:41], off offset:3072
	s_nop 0
	global_load_dwordx4 v[24:27], v[60:61], off offset:3072
	s_waitcnt vmcnt(0)
	v_pk_add_f32 v[26:27], v[26:27], 1.0 op_sel_hi:[1,0]
	v_pk_add_f32 v[24:25], v[24:25], 1.0 op_sel_hi:[1,0]
	v_pk_mul_f32 v[26:27], v[22:23], v[26:27]
	v_pk_mul_f32 v[24:25], v[20:21], v[24:25]
	global_load_dwordx4 v[20:23], v[58:59], off offset:3072
	s_waitcnt vmcnt(0)
	v_pk_fma_f32 v[16:17], v[18:19], v[24:25], v[20:21]
	v_pk_fma_f32 v[8:9], v[8:9], v[24:25], v[20:21]
	v_pk_fma_f32 v[2:3], v[2:3], v[26:27], v[22:23]
	v_pk_fma_f32 v[6:7], v[6:7], v[24:25], v[20:21]
	v_pk_fma_f32 v[14:15], v[14:15], v[26:27], v[22:23]
	v_cvt_pk_bf16_f32 v16, v16, v17
	v_pk_fma_f32 v[10:11], v[10:11], v[26:27], v[22:23]
	v_cvt_pk_bf16_f32 v17, v14, v15
	global_store_dwordx2 v[62:63], v[16:17], off offset:-2560
	v_cvt_pk_bf16_f32 v8, v8, v9
	v_cvt_pk_bf16_f32 v9, v10, v11
	global_store_dwordx2 v[62:63], v[8:9], off offset:-512
	v_cvt_pk_bf16_f32 v6, v6, v7
	v_cvt_pk_bf16_f32 v7, v2, v3
	v_pk_mul_f32 v[2:3], v[4:5], v[28:29] op_sel_hi:[1,0]
	global_store_dwordx2 v[64:65], v[6:7], off offset:-2560
	v_pk_fma_f32 v[2:3], v[2:3], v[24:25], v[20:21]
	v_pk_fma_f32 v[0:1], v[0:1], v[26:27], v[22:23]
	v_cvt_pk_bf16_f32 v2, v2, v3
	s_nop 0
	v_cvt_pk_bf16_f32 v3, v0, v1
	global_store_dwordx2 v[64:65], v[2:3], off offset:-512
	s_cbranch_scc0 .LBB0_653

;     ...
;     f32x4 x[NR][4];
; #pragma unroll
;     for (int r = 0; r < NR; ++r)
; #pragma unroll
;         for (int j = 0; j < 4; ++j) x[r][j] = *(const f32x4*)(xin + (size_t)r * DM + j * 256 + lane * 4);
;     if (upd) {
;         f32x4 y[NR][4];
; #pragma unroll
;         for (int r = 0; r < NR; ++r)
; #pragma unroll
;             for (int j = 0; j < 4; ++j) {
;                 if (NP == 0) { const v2u w = *(const v2u*)(upd + (size_t)r * DM + j * 256 + lane * 4); y[r][j][0] = bflo(w.x); y[r][j][1] = bfhi(w.x); y[r][j][2] = bflo(w.y); y[r][j][3] = bfhi(w.y); }
;                 else { const float* pp = (const float*)upd + (size_t)r * DM + j * 256 + lane * 4; f32x4 t = *(const f32x4*)pp;
; #pragma unroll
;                     for (int p = 1; p < NP; ++p) t = t + *(const f32x4*)(pp + (size_t)p * 2048 * 1024);
;                     y[r][j] = t; } }
;         float rr[NR];
; #pragma unroll
;         for (int r = 0; r < NR; ++r) { float ss = 0.f;
; #pragma unroll
;             for (int j = 0; j < 4; ++j) ss += (y[r][j][0] * y[r][j][0] + y[r][j][1] * y[r][j][1]) + (y[r][j][2] * y[r][j][2] + y[r][j][3] * y[r][j][3]);
;             rr[r] = ss; }
; __global__ void __launch_bounds__(512, 2) fwd_megakernel(Args a) {
;     ...
;         for (int row = gw * (ML / NGW), rend = row + ML / NGW; row < rend; row += 4) {
;             const int mr = row >> 13; const float* md = modl + (size_t)mr * 6144;
;             const float* xin = l == 0 ? a.in[0] + (size_t)row * DM : a.out + (size_t)row * DM;
;             if (!last) { const float* mdn = MOD + (size_t)(9 + mr) * 6144;
;                 row_op<4>(xin, YB + (size_t)row * DM, md + 2048, a.in[14] + l * 1024, a.out + (size_t)row * DM, HX + (size_t)row * DM, a.in[6] + 1024, mdn + 1024, mdn, lane,
.LBB0_874:
	s_ashr_i32 s8, s18, 13
	s_mul_i32 s4, s8, 0x1800
	s_ashr_i32 s5, s4, 31
	s_lshl_b64 s[4:5], s[4:5], 2
	s_add_u32 s34, s42, s4
	s_addc_u32 s35, s43, s5
	s_and_b64 vcc, exec, s[14:15]
	s_mov_b64 s[4:5], -1
	s_cbranch_vccnz .LBB0_878
	v_mov_b32_e32 v0, v228
	s_add_u32 s4, s16, s78
	v_lshlrev_b32_e32 v64, 2, v0
	v_ashrrev_i32_e32 v65, 31, v64
	v_lshlrev_b64 v[66:67], 2, v[64:65]
	s_addc_u32 s5, s17, s79
	v_lshl_add_u64 v[12:13], s[4:5], 0, v[66:67]
	v_add_co_u32_e32 v4, vcc, s75, v12
	global_load_dwordx4 v[48:51], v[12:13], off nt
	global_load_dwordx4 v[32:35], v[12:13], off offset:1024 nt
	global_load_dwordx4 v[16:19], v[12:13], off offset:2048 nt
	global_load_dwordx4 v[0:3], v[12:13], off offset:3072 nt
	v_addc_co_u32_e32 v5, vcc, 0, v13, vcc
	v_add_co_u32_e32 v6, vcc, s28, v12
	v_lshl_add_u64 v[64:65], v[64:65], 1, s[26:27]
	s_nop 0
	v_addc_co_u32_e32 v7, vcc, 0, v13, vcc
	v_add_co_u32_e32 v12, vcc, s38, v12
	global_load_dwordx4 v[52:55], v[6:7], off offset:-4096 nt
	global_load_dwordx4 v[44:47], v[4:5], off offset:1024 nt
	global_load_dwordx4 v[20:23], v[4:5], off offset:2048 nt
	global_load_dwordx4 v[8:11], v[4:5], off offset:3072 nt
	global_load_dwordx4 v[56:59], v[6:7], off nt
	global_load_dwordx4 v[36:39], v[6:7], off offset:1024 nt
	global_load_dwordx4 v[24:27], v[6:7], off offset:2048 nt
	s_nop 0
	global_load_dwordx4 v[4:7], v[6:7], off offset:3072 nt
	v_addc_co_u32_e32 v13, vcc, 0, v13, vcc
	global_load_dwordx4 v[60:63], v[12:13], off nt
	global_load_dwordx4 v[40:43], v[12:13], off offset:1024 nt
	global_load_dwordx4 v[28:31], v[12:13], off offset:2048 nt
	s_nop 0
	global_load_dwordx4 v[12:15], v[12:13], off offset:3072 nt
	s_waitcnt lgkmcnt(0)
	global_load_dwordx2 v[100:101], v[64:65], off
	global_load_dwordx2 v[94:95], v[64:65], off offset:512
	global_load_dwordx2 v[102:103], v[64:65], off offset:1024
	global_load_dwordx2 v[72:73], v[64:65], off offset:1536
	global_load_dwordx2 v[104:105], v[64:65], off offset:2048
	global_load_dwordx2 v[110:111], v[64:65], off offset:2560
	global_load_dwordx2 v[112:113], v[64:65], off offset:3072
	global_load_dwordx2 v[78:79], v[64:65], off offset:3584
	v_add_co_u32_e32 v86, vcc, s75, v64
	s_mov_b64 s[4:5], 0x2000
	s_nop 0
	v_addc_co_u32_e32 v87, vcc, 0, v65, vcc
	global_load_dwordx2 v[124:125], v[86:87], off
	global_load_dwordx2 v[118:119], v[86:87], off offset:512
	global_load_dwordx2 v[120:121], v[86:87], off offset:1024
	global_load_dwordx2 v[84:85], v[86:87], off offset:1536
	global_load_dwordx2 v[122:123], v[86:87], off offset:2048
	global_load_dwordx2 v[96:97], v[86:87], off offset:2560
	global_load_dwordx2 v[88:89], v[86:87], off offset:3072
	global_load_dwordx2 v[92:93], v[86:87], off offset:3584
	s_waitcnt vmcnt(15)
	v_lshlrev_b32_e32 v98, 16, v100
	v_and_b32_e32 v99, 0xffff0000, v100
	v_lshlrev_b32_e32 v100, 16, v101
	v_and_b32_e32 v101, 0xffff0000, v101
	s_waitcnt vmcnt(12)
	v_and_b32_e32 v69, 0xffff0000, v72
	v_mul_f32_e32 v68, v101, v101
	v_and_b32_e32 v115, 0xffff0000, v95
	v_and_b32_e32 v114, 0xffff0000, v94
	v_pk_fma_f32 v[116:117], v[100:101], v[100:101], v[68:69] op_sel_hi:[1,1,0]
	v_lshlrev_b32_e32 v107, 16, v95
	v_lshlrev_b32_e32 v106, 16, v94
	v_pk_mul_f32 v[94:95], v[114:115], v[114:115]
	v_mul_f32_e32 v68, v99, v99
	v_lshlrev_b32_e32 v71, 16, v72
	v_pk_fma_f32 v[126:127], v[106:107], v[106:107], v[94:95]
	v_lshlrev_b32_e32 v94, 16, v102
	v_and_b32_e32 v95, 0xffff0000, v102
	v_lshlrev_b32_e32 v108, 16, v103
	v_and_b32_e32 v109, 0xffff0000, v103
	v_pk_fma_f32 v[102:103], v[98:99], v[98:99], v[68:69] op_sel_hi:[1,1,0]
	v_mov_b32_e32 v128, v116
	v_mov_b32_e32 v70, v102
	v_mov_b32_e32 v129, v71
	v_pk_add_f32 v[102:103], v[102:103], v[116:117]
	v_pk_mul_f32 v[116:117], v[70:71], v[128:129]
	v_mul_f32_e32 v74, v69, v69
	v_mov_b32_e32 v103, v117
	v_pk_add_f32 v[116:117], v[126:127], v[126:127] op_sel:[0,1] op_sel_hi:[1,0]
	v_mul_f32_e32 v68, v95, v95
	v_mov_b32_e32 v117, v74
	v_lshlrev_b32_e32 v72, 16, v73
	v_and_b32_e32 v73, 0xffff0000, v73
	v_pk_add_f32 v[102:103], v[102:103], v[116:117]
	v_pk_fma_f32 v[116:117], v[94:95], v[94:95], v[68:69] op_sel_hi:[1,1,0]
	v_mul_f32_e32 v68, v109, v109
	v_mul_f32_e32 v76, v72, v72
	v_mul_f32_e32 v80, v73, v73
	v_pk_fma_f32 v[126:127], v[108:109], v[108:109], v[68:69] op_sel_hi:[1,1,0]
	v_mov_b32_e32 v117, v76
	v_mov_b32_e32 v127, v80
	v_pk_add_f32 v[116:117], v[116:117], v[126:127]
	s_waitcnt vmcnt(10)
	v_and_b32_e32 v127, 0xffff0000, v111
	v_pk_add_f32 v[136:137], v[102:103], v[116:117]
	v_lshlrev_b32_e32 v102, 16, v104
	v_and_b32_e32 v103, 0xffff0000, v104
	v_lshlrev_b32_e32 v104, 16, v105
	v_and_b32_e32 v105, 0xffff0000, v105
	v_mul_f32_e32 v68, v105, v105
	v_pk_fma_f32 v[128:129], v[104:105], v[104:105], v[68:69] op_sel_hi:[1,1,0]
	v_and_b32_e32 v126, 0xffff0000, v110
	v_mul_f32_e32 v68, v103, v103
	s_waitcnt vmcnt(8)
	v_lshlrev_b32_e32 v77, 16, v78
	v_lshlrev_b32_e32 v117, 16, v111
	v_lshlrev_b32_e32 v116, 16, v110
	v_pk_mul_f32 v[110:111], v[126:127], v[126:127]
	v_pk_fma_f32 v[132:133], v[102:103], v[102:103], v[68:69] op_sel_hi:[1,1,0]
	v_and_b32_e32 v75, 0xffff0000, v78
	v_pk_fma_f32 v[130:131], v[116:117], v[116:117], v[110:111]
	v_mov_b32_e32 v76, v132
	v_mov_b32_e32 v134, v128
	v_mov_b32_e32 v135, v77
	v_and_b32_e32 v111, 0xffff0000, v112
	v_mul_f32_e32 v70, v75, v75
	v_pk_add_f32 v[128:129], v[132:133], v[128:129]
	v_pk_mul_f32 v[132:133], v[76:77], v[134:135]
	v_pk_add_f32 v[130:131], v[130:131], v[130:131] op_sel:[0,1] op_sel_hi:[1,0]
	v_lshlrev_b32_e32 v110, 16, v112
	v_lshlrev_b32_e32 v112, 16, v113
	v_and_b32_e32 v113, 0xffff0000, v113
	v_mov_b32_e32 v129, v133
	v_mov_b32_e32 v131, v70
	v_mul_f32_e32 v68, v111, v111
	v_lshlrev_b32_e32 v78, 16, v79
	v_and_b32_e32 v79, 0xffff0000, v79
	v_pk_add_f32 v[128:129], v[128:129], v[130:131]
	v_pk_fma_f32 v[130:131], v[110:111], v[110:111], v[68:69] op_sel_hi:[1,1,0]
	v_mul_f32_e32 v68, v113, v113
	v_mul_f32_e32 v74, v78, v78
	v_mul_f32_e32 v80, v79, v79
	v_pk_fma_f32 v[132:133], v[112:113], v[112:113], v[68:69] op_sel_hi:[1,1,0]
	v_mov_b32_e32 v131, v74
	v_mov_b32_e32 v133, v80
	s_waitcnt vmcnt(7)
;     ...
;                 if (NP == 0) { const v2u w = *(const v2u*)(upd + (size_t)r * DM + j * 256 + lane * 4); y[r][j][0] = bflo(w.x); y[r][j][1] = bfhi(w.x); y[r][j][2] = bflo(w.y); y[r][j][3] = bfhi(w.y); }
;                 else { const float* pp = (const float*)upd + (size_t)r * DM + j * 256 + lane * 4; f32x4 t = *(const f32x4*)pp;
; #pragma unroll
;                     for (int p = 1; p < NP; ++p) t = t + *(const f32x4*)(pp + (size_t)p * 2048 * 1024);
;                     y[r][j] = t; } }
;         float rr[NR];
; #pragma unroll
;         for (int r = 0; r < NR; ++r) { float ss = 0.f;
; #pragma unroll
;             for (int j = 0; j < 4; ++j) ss += (y[r][j][0] * y[r][j][0] + y[r][j][1] * y[r][j][1]) + (y[r][j][2] * y[r][j][2] + y[r][j][3] * y[r][j][3]);
;             rr[r] = ss; }
; #pragma unroll
;         for (int r = 0; r < NR; ++r) rr[r] = rsqrtf(wave_sum(rr[r]) * (1.f / 1024.f) + EPSN);
	v_and_b32_e32 v143, 0xffff0000, v125
	v_pk_add_f32 v[130:131], v[130:131], v[132:133]
	v_and_b32_e32 v141, 0xffff0000, v124
	v_lshlrev_b32_e32 v142, 16, v125
	v_mul_f32_e32 v68, v143, v143
	v_pk_add_f32 v[138:139], v[128:129], v[130:131]
	v_lshlrev_b32_e32 v140, 16, v124
	v_pk_fma_f32 v[124:125], v[142:143], v[142:143], v[68:69] op_sel_hi:[1,1,0]
	s_waitcnt vmcnt(6)
	v_and_b32_e32 v131, 0xffff0000, v119
	v_and_b32_e32 v130, 0xffff0000, v118
	v_mul_f32_e32 v68, v141, v141
	s_waitcnt vmcnt(4)
	v_lshlrev_b32_e32 v83, 16, v84
	v_lshlrev_b32_e32 v129, 16, v119
	v_lshlrev_b32_e32 v128, 16, v118
	v_pk_mul_f32 v[118:119], v[130:131], v[130:131]
	v_pk_fma_f32 v[134:135], v[140:141], v[140:141], v[68:69] op_sel_hi:[1,1,0]
	v_and_b32_e32 v81, 0xffff0000, v84
	v_pk_fma_f32 v[132:133], v[128:129], v[128:129], v[118:119]
	v_mov_b32_e32 v82, v134
	v_mov_b32_e32 v144, v124
	v_mov_b32_e32 v145, v83
	v_and_b32_e32 v119, 0xffff0000, v120
	v_mul_f32_e32 v70, v81, v81
	v_pk_add_f32 v[124:125], v[134:135], v[124:125]
	v_pk_mul_f32 v[134:135], v[82:83], v[144:145]
	v_pk_add_f32 v[132:133], v[132:133], v[132:133] op_sel:[0,1] op_sel_hi:[1,0]
	v_lshlrev_b32_e32 v118, 16, v120
	v_lshlrev_b32_e32 v120, 16, v121
	v_and_b32_e32 v121, 0xffff0000, v121
	v_mov_b32_e32 v125, v135
	v_mov_b32_e32 v133, v70
	v_mul_f32_e32 v68, v119, v119
	v_lshlrev_b32_e32 v84, 16, v85
	v_and_b32_e32 v85, 0xffff0000, v85
	v_pk_add_f32 v[124:125], v[124:125], v[132:133]
	v_pk_fma_f32 v[132:133], v[118:119], v[118:119], v[68:69] op_sel_hi:[1,1,0]
	v_mul_f32_e32 v68, v121, v121
	v_mul_f32_e32 v74, v84, v84
	v_mul_f32_e32 v76, v85, v85
	v_pk_fma_f32 v[134:135], v[120:121], v[120:121], v[68:69] op_sel_hi:[1,1,0]
	s_waitcnt vmcnt(3)
	v_and_b32_e32 v147, 0xffff0000, v123
	v_mov_b32_e32 v133, v74
	v_mov_b32_e32 v135, v76
	v_and_b32_e32 v145, 0xffff0000, v122
	v_lshlrev_b32_e32 v146, 16, v123
	v_mul_f32_e32 v68, v147, v147
	v_pk_add_f32 v[132:133], v[132:133], v[134:135]
	v_lshlrev_b32_e32 v144, 16, v122
	v_pk_fma_f32 v[150:151], v[146:147], v[146:147], v[68:69] op_sel_hi:[1,1,0]
	s_waitcnt vmcnt(2)
	v_and_b32_e32 v135, 0xffff0000, v97
	v_and_b32_e32 v134, 0xffff0000, v96
	v_mul_f32_e32 v68, v145, v145
	s_waitcnt vmcnt(0)
	v_lshlrev_b32_e32 v91, 16, v92
	v_pk_add_f32 v[148:149], v[124:125], v[132:133]
	v_lshlrev_b32_e32 v133, 16, v97
	v_lshlrev_b32_e32 v132, 16, v96
	v_pk_mul_f32 v[96:97], v[134:135], v[134:135]
	v_lshlrev_b32_e32 v122, 16, v88
	v_and_b32_e32 v123, 0xffff0000, v88
	v_lshlrev_b32_e32 v124, 16, v89
	v_and_b32_e32 v125, 0xffff0000, v89
	v_pk_fma_f32 v[88:89], v[144:145], v[144:145], v[68:69] op_sel_hi:[1,1,0]
	v_and_b32_e32 v87, 0xffff0000, v92
	v_pk_fma_f32 v[96:97], v[132:133], v[132:133], v[96:97]
	v_mov_b32_e32 v90, v88
	v_mov_b32_e32 v152, v150
	v_mov_b32_e32 v153, v91
	v_mul_f32_e32 v70, v87, v87
	v_pk_add_f32 v[88:89], v[88:89], v[150:151]
	v_pk_mul_f32 v[150:151], v[90:91], v[152:153]
	v_pk_add_f32 v[96:97], v[96:97], v[96:97] op_sel:[0,1] op_sel_hi:[1,0]
	v_mov_b32_e32 v89, v151
	v_mov_b32_e32 v97, v70
	v_mul_f32_e32 v68, v123, v123
	v_lshlrev_b32_e32 v92, 16, v93
	v_and_b32_e32 v93, 0xffff0000, v93
	v_pk_add_f32 v[88:89], v[88:89], v[96:97]
	v_pk_fma_f32 v[96:97], v[122:123], v[122:123], v[68:69] op_sel_hi:[1,1,0]
	v_mul_f32_e32 v68, v125, v125
	v_mul_f32_e32 v74, v92, v92
	v_mul_f32_e32 v76, v93, v93
	v_pk_fma_f32 v[150:151], v[124:125], v[124:125], v[68:69] op_sel_hi:[1,1,0]
	v_and_b32_e32 v68, 64, v232
	v_mov_b32_e32 v97, v74
	v_mov_b32_e32 v151, v76
	v_add_u32_e32 v68, 64, v68
	v_xor_b32_e32 v70, 1, v232
	v_pk_add_f32 v[96:97], v[96:97], v[150:151]
	v_cmp_lt_i32_e32 vcc, v70, v68
	v_pk_add_f32 v[96:97], v[88:89], v[96:97]
	v_mov_b32_e32 v88, v138
	v_cndmask_b32_e32 v70, v232, v70, vcc
	v_mov_b32_e32 v89, v136
	v_mov_b32_e32 v136, v139
	v_lshlrev_b32_e32 v161, 2, v70
	v_pk_add_f32 v[88:89], v[88:89], v[136:137]
	ds_bpermute_b32 v137, v161, v89
	ds_bpermute_b32 v136, v161, v88
	v_xor_b32_e32 v70, 2, v232
	v_cmp_lt_i32_e32 vcc, v70, v68
	v_lshl_add_u64 v[138:139], s[0:1], 0, v[66:67]
	v_mov_b32_e32 v80, v83
	v_cndmask_b32_e32 v70, v232, v70, vcc
	v_lshlrev_b32_e32 v160, 2, v70
	s_waitcnt lgkmcnt(0)
	v_pk_add_f32 v[88:89], v[88:89], v[136:137]
	ds_bpermute_b32 v137, v160, v89
	ds_bpermute_b32 v136, v160, v88
	v_xor_b32_e32 v70, 4, v232
	v_cmp_lt_i32_e32 vcc, v70, v68
	v_mov_b32_e32 v86, v91
	s_waitcnt lgkmcnt(0)
	v_pk_add_f32 v[88:89], v[88:89], v[136:137]
	v_cndmask_b32_e32 v70, v232, v70, vcc
	v_lshlrev_b32_e32 v159, 2, v70
	ds_bpermute_b32 v137, v159, v89
	ds_bpermute_b32 v136, v159, v88
	v_xor_b32_e32 v70, 8, v232
	v_cmp_lt_i32_e32 vcc, v70, v68
	s_waitcnt lgkmcnt(0)
	v_pk_add_f32 v[88:89], v[88:89], v[136:137]
	v_cndmask_b32_e32 v70, v232, v70, vcc
	v_lshlrev_b32_e32 v158, 2, v70
	ds_bpermute_b32 v137, v158, v89
	ds_bpermute_b32 v136, v158, v88
	v_xor_b32_e32 v70, 16, v232
	v_cmp_lt_i32_e32 vcc, v70, v68
	s_waitcnt lgkmcnt(0)
	v_pk_add_f32 v[88:89], v[88:89], v[136:137]
	v_cndmask_b32_e32 v70, v232, v70, vcc
	v_lshlrev_b32_e32 v157, 2, v70
	ds_bpermute_b32 v137, v157, v89
	ds_bpermute_b32 v136, v157, v88
	v_xor_b32_e32 v70, 32, v232
	v_cmp_lt_i32_e32 vcc, v70, v68
	s_waitcnt lgkmcnt(0)
	v_pk_add_f32 v[88:89], v[88:89], v[136:137]
	v_cndmask_b32_e32 v68, v232, v70, vcc
	v_lshlrev_b32_e32 v156, 2, v68
	ds_bpermute_b32 v137, v156, v89
	ds_bpermute_b32 v136, v156, v88
	s_waitcnt lgkmcnt(0)
;     ...
;         for (int r = 0; r < NR; ++r) rr[r] = rsqrtf(wave_sum(rr[r]) * (1.f / 1024.f) + EPSN);
; #pragma unroll
;         for (int j = 0; j < 4; ++j) { const f32x4 g = *(const f32x4*)(gate + j * 256 + lane * 4) * *(const f32x4*)(gupd + j * 256 + lane * 4);
; #pragma unroll
;             for (int r = 0; r < NR; ++r) x[r][j] = x[r][j] + g * (y[r][j] * rr[r]); }
	v_pk_add_f32 v[136:137], v[88:89], v[136:137]
	v_mov_b64_e32 v[88:89], s[48:49]
	v_pk_fma_f32 v[136:137], v[136:137], s[72:73], v[88:89] op_sel_hi:[1,0,0]
	s_nop 0
	v_mul_f32_e32 v68, 0x4b800000, v137
	v_cmp_gt_f32_e64 s[6:7], s29, v137
	v_cmp_gt_f32_e32 vcc, s29, v136
	s_nop 0
	v_cndmask_b32_e64 v68, v137, v68, s[6:7]
	v_rsq_f32_e32 v68, v68
	v_mov_b32_e32 v137, v148
	v_mov_b32_e32 v148, v97
	v_mul_f32_e32 v70, 0x45800000, v68
	v_cndmask_b32_e64 v70, v68, v70, s[6:7]
	v_mul_f32_e32 v68, 0x4b800000, v136
	v_cndmask_b32_e32 v68, v136, v68, vcc
	v_mov_b32_e32 v136, v96
	v_pk_add_f32 v[96:97], v[136:137], v[148:149]
	ds_bpermute_b32 v137, v161, v97
	ds_bpermute_b32 v136, v161, v96
	v_rsq_f32_e32 v68, v68
	v_pk_mul_f32 v[100:101], v[70:71], v[100:101] op_sel_hi:[0,1]
	v_pk_mul_f32 v[98:99], v[70:71], v[98:99] op_sel_hi:[0,1]
	s_waitcnt lgkmcnt(0)
	v_pk_add_f32 v[96:97], v[96:97], v[136:137]
	ds_bpermute_b32 v137, v160, v97
	ds_bpermute_b32 v136, v160, v96
	v_mul_f32_e32 v74, 0x45800000, v68
	v_cndmask_b32_e32 v76, v68, v74, vcc
	s_waitcnt lgkmcnt(0)
	v_pk_add_f32 v[96:97], v[96:97], v[136:137]
	ds_bpermute_b32 v137, v159, v97
	ds_bpermute_b32 v136, v159, v96
	s_waitcnt lgkmcnt(0)
	v_pk_add_f32 v[96:97], v[96:97], v[136:137]
	ds_bpermute_b32 v137, v158, v97
	ds_bpermute_b32 v136, v158, v96
	s_waitcnt lgkmcnt(0)
	v_pk_add_f32 v[96:97], v[96:97], v[136:137]
	ds_bpermute_b32 v137, v157, v97
	ds_bpermute_b32 v136, v157, v96
	s_waitcnt lgkmcnt(0)
	v_pk_add_f32 v[96:97], v[96:97], v[136:137]
	ds_bpermute_b32 v137, v156, v97
	ds_bpermute_b32 v136, v156, v96
	s_waitcnt lgkmcnt(0)
	v_pk_add_f32 v[96:97], v[96:97], v[136:137]
	s_nop 0
	v_pk_fma_f32 v[96:97], v[96:97], s[72:73], v[88:89] op_sel_hi:[1,0,0]
	s_nop 0
	v_mul_f32_e32 v68, 0x4b800000, v97
	v_cmp_gt_f32_e64 s[6:7], s29, v97
	v_cmp_gt_f32_e32 vcc, s29, v96
	s_nop 0
	v_cndmask_b32_e64 v68, v97, v68, s[6:7]
	v_rsq_f32_e32 v68, v68
	s_nop 0
	v_mul_f32_e32 v74, 0x45800000, v68
	v_cndmask_b32_e64 v82, v68, v74, s[6:7]
	v_mul_f32_e32 v68, 0x4b800000, v96
	v_cndmask_b32_e32 v68, v96, v68, vcc
	v_rsq_f32_e32 v68, v68
	v_lshl_add_u64 v[96:97], s[34:35], 0, v[66:67]
	v_lshl_add_u64 v[136:137], v[96:97], 0, s[4:5]
	s_mov_b64 s[4:5], 0x5000
	v_mul_f32_e32 v74, 0x45800000, v68
	v_cndmask_b32_e32 v90, v68, v74, vcc
	v_add_co_u32_e32 v148, vcc, s28, v96
	v_mov_b32_e32 v68, v71
	s_nop 0
	v_addc_co_u32_e32 v149, vcc, 0, v97, vcc
	global_load_dwordx4 v[148:151], v[148:149], off
	s_nop 0
	global_load_dwordx4 v[152:155], v[138:139], off
	v_mov_b32_e32 v74, v77
	s_waitcnt vmcnt(0)
	v_pk_mul_f32 v[150:151], v[150:151], v[154:155]
	v_pk_mul_f32 v[148:149], v[148:149], v[152:153]
	s_nop 0
	v_pk_fma_f32 v[48:49], v[98:99], v[148:149], v[48:49]
	v_pk_fma_f32 v[98:99], v[100:101], v[150:151], v[50:51]
	v_pk_mul_f32 v[100:101], v[76:77], v[104:105] op_sel_hi:[0,1]
	v_pk_mul_f32 v[50:51], v[76:77], v[102:103] op_sel_hi:[0,1]
	v_pk_fma_f32 v[50:51], v[50:51], v[148:149], v[52:53]
	v_pk_fma_f32 v[100:101], v[100:101], v[150:151], v[54:55]
	v_pk_mul_f32 v[54:55], v[82:83], v[142:143] op_sel_hi:[0,1]
	v_pk_mul_f32 v[52:53], v[82:83], v[140:141] op_sel_hi:[0,1]
	v_pk_fma_f32 v[52:53], v[148:149], v[52:53], v[56:57]
	v_pk_fma_f32 v[102:103], v[150:151], v[54:55], v[58:59]
	v_pk_mul_f32 v[56:57], v[90:91], v[146:147] op_sel_hi:[0,1]
	v_pk_mul_f32 v[54:55], v[90:91], v[144:145] op_sel_hi:[0,1]
	v_pk_fma_f32 v[54:55], v[148:149], v[54:55], v[60:61]
	v_pk_fma_f32 v[104:105], v[150:151], v[56:57], v[62:63]
	global_load_dwordx4 v[56:59], v[136:137], off offset:1024
	global_load_dwordx4 v[60:63], v[138:139], off offset:1024
	s_waitcnt vmcnt(0)
	v_pk_mul_f32 v[56:57], v[56:57], v[60:61]
	v_mov_b32_e32 v60, v107
	v_mov_b32_e32 v61, v115
	v_pk_mul_f32 v[58:59], v[58:59], v[62:63]
	v_pk_mul_f32 v[60:61], v[70:71], v[60:61] op_sel_hi:[0,1]
	v_mov_b32_e32 v107, v114
	v_pk_mul_f32 v[62:63], v[70:71], v[106:107] op_sel_hi:[0,1]
	v_pk_fma_f32 v[106:107], v[60:61], v[58:59], v[34:35]
	v_mov_b32_e32 v34, v117
	v_mov_b32_e32 v35, v127
	v_mov_b32_e32 v117, v126
	v_pk_mul_f32 v[60:61], v[76:77], v[34:35] op_sel_hi:[0,1]
	v_pk_mul_f32 v[34:35], v[76:77], v[116:117] op_sel_hi:[0,1]
	v_pk_fma_f32 v[34:35], v[34:35], v[56:57], v[44:45]
	v_pk_fma_f32 v[44:45], v[60:61], v[58:59], v[46:47]
	v_mov_b32_e32 v46, v129
	v_mov_b32_e32 v47, v131
	v_pk_mul_f32 v[46:47], v[82:83], v[46:47] op_sel_hi:[0,1]
	v_mov_b32_e32 v129, v130
	v_pk_mul_f32 v[60:61], v[82:83], v[128:129] op_sel_hi:[0,1]
	v_pk_fma_f32 v[46:47], v[58:59], v[46:47], v[38:39]
	v_mov_b32_e32 v38, v133
	v_mov_b32_e32 v39, v135
	v_mov_b32_e32 v133, v134
	v_pk_fma_f32 v[36:37], v[56:57], v[60:61], v[36:37]
	v_pk_mul_f32 v[60:61], v[90:91], v[38:39] op_sel_hi:[0,1]
	v_pk_mul_f32 v[38:39], v[90:91], v[132:133] op_sel_hi:[0,1]
	v_pk_fma_f32 v[32:33], v[62:63], v[56:57], v[32:33]
	v_pk_fma_f32 v[38:39], v[56:57], v[38:39], v[40:41]
	v_pk_fma_f32 v[40:41], v[58:59], v[60:61], v[42:43]
	global_load_dwordx4 v[56:59], v[136:137], off offset:2048
	global_load_dwordx4 v[60:63], v[138:139], off offset:2048
	v_pk_mul_f32 v[42:43], v[70:71], v[94:95] op_sel_hi:[0,1]
	s_waitcnt vmcnt(0)
;     ...
;         for (int j = 0; j < 4; ++j) { const f32x4 g = *(const f32x4*)(gate + j * 256 + lane * 4) * *(const f32x4*)(gupd + j * 256 + lane * 4);
; #pragma unroll
;             for (int r = 0; r < NR; ++r) x[r][j] = x[r][j] + g * (y[r][j] * rr[r]); }
;     }
;     if (upd2) {
;         f32x4 y[NR][4];
; #pragma unroll
;         for (int r = 0; r < NR; ++r)
; #pragma unroll
;             for (int j = 0; j < 4; ++j) { const v2u w = *(const v2u*)(upd2 + (size_t)r * DM + j * 256 + lane * 4); y[r][j][0] = bflo(w.x); y[r][j][1] = bfhi(w.x); y[r][j][2] = bflo(w.y); y[r][j][3] = bfhi(w.y); }
	v_pk_mul_f32 v[58:59], v[58:59], v[62:63]
	v_pk_mul_f32 v[56:57], v[56:57], v[60:61]
	v_pk_mul_f32 v[60:61], v[70:71], v[108:109] op_sel_hi:[0,1]
	v_pk_fma_f32 v[42:43], v[42:43], v[56:57], v[16:17]
	v_pk_fma_f32 v[114:115], v[60:61], v[58:59], v[18:19]
	v_pk_mul_f32 v[16:17], v[76:77], v[112:113] op_sel_hi:[0,1]
	v_pk_mul_f32 v[18:19], v[76:77], v[110:111] op_sel_hi:[0,1]
	v_pk_fma_f32 v[108:109], v[18:19], v[56:57], v[20:21]
	v_pk_fma_f32 v[116:117], v[16:17], v[58:59], v[22:23]
	v_pk_mul_f32 v[16:17], v[82:83], v[120:121] op_sel_hi:[0,1]
	v_pk_mul_f32 v[18:19], v[82:83], v[118:119] op_sel_hi:[0,1]
	v_pk_fma_f32 v[110:111], v[18:19], v[56:57], v[24:25]
	v_pk_fma_f32 v[118:119], v[16:17], v[58:59], v[26:27]
	v_pk_mul_f32 v[16:17], v[90:91], v[124:125] op_sel_hi:[0,1]
	v_pk_mul_f32 v[18:19], v[90:91], v[122:123] op_sel_hi:[0,1]
	v_pk_fma_f32 v[112:113], v[56:57], v[18:19], v[28:29]
	v_pk_fma_f32 v[120:121], v[58:59], v[16:17], v[30:31]
	global_load_dwordx4 v[16:19], v[136:137], off offset:3072
	global_load_dwordx4 v[20:23], v[138:139], off offset:3072
	s_waitcnt vmcnt(0)
	v_pk_mul_f32 v[18:19], v[18:19], v[22:23]
	v_pk_mul_f32 v[16:17], v[16:17], v[20:21]
	v_pk_mul_f32 v[22:23], v[70:71], v[68:69] op_sel_hi:[0,1]
	v_pk_fma_f32 v[60:61], v[22:23], v[16:17], v[0:1]
	v_pk_mul_f32 v[0:1], v[76:77], v[78:79] op_sel_hi:[0,1]
	v_pk_mul_f32 v[20:21], v[70:71], v[72:73] op_sel_hi:[0,1]
	v_pk_fma_f32 v[58:59], v[0:1], v[18:19], v[10:11]
	v_pk_mul_f32 v[0:1], v[82:83], v[84:85] op_sel_hi:[0,1]
	v_pk_fma_f32 v[62:63], v[20:21], v[18:19], v[2:3]
	v_pk_mul_f32 v[2:3], v[76:77], v[74:75] op_sel_hi:[0,1]
	v_pk_fma_f32 v[74:75], v[0:1], v[18:19], v[6:7]
	v_pk_mul_f32 v[0:1], v[90:91], v[92:93] op_sel_hi:[0,1]
	v_pk_fma_f32 v[56:57], v[2:3], v[16:17], v[8:9]
	v_pk_mul_f32 v[2:3], v[82:83], v[80:81] op_sel_hi:[0,1]
	v_pk_fma_f32 v[70:71], v[18:19], v[0:1], v[14:15]
	v_add_co_u32_e32 v0, vcc, s39, v64
	v_pk_fma_f32 v[72:73], v[2:3], v[16:17], v[4:5]
	v_pk_mul_f32 v[2:3], v[90:91], v[86:87] op_sel_hi:[0,1]
	v_addc_co_u32_e32 v1, vcc, -1, v65, vcc
	v_pk_fma_f32 v[68:69], v[16:17], v[2:3], v[12:13]
	global_load_dwordx2 v[2:3], v[0:1], off offset:-4096
	global_load_dwordx2 v[18:19], v[0:1], off offset:-3584
	global_load_dwordx2 v[4:5], v[0:1], off offset:-3072
	global_load_dwordx2 v[6:7], v[0:1], off offset:-2560
	s_waitcnt vmcnt(1)
	v_lshlrev_b32_e32 v128, 16, v4
	s_waitcnt vmcnt(0)
	v_lshlrev_b32_e32 v81, 16, v6
	v_and_b32_e32 v79, 0xffff0000, v6
	v_lshlrev_b32_e32 v76, 16, v7
	v_and_b32_e32 v77, 0xffff0000, v7
	global_load_dwordx2 v[6:7], v[0:1], off offset:-2048
	global_load_dwordx2 v[22:23], v[0:1], off offset:-1536
	global_load_dwordx2 v[24:25], v[0:1], off offset:-1024
	global_load_dwordx2 v[8:9], v[0:1], off offset:-512
	global_load_dwordx2 v[14:15], v[0:1], off
	v_add_co_u32_e32 v0, vcc, s46, v64
	v_and_b32_e32 v129, 0xffff0000, v4
	s_nop 0
	v_addc_co_u32_e32 v1, vcc, -1, v65, vcc
	v_lshlrev_b32_e32 v130, 16, v5
	v_and_b32_e32 v131, 0xffff0000, v5
	v_mov_b32_e32 v133, v81
	v_mul_f32_e32 v78, v79, v79
	v_mul_f32_e32 v84, v76, v76
	v_mul_f32_e32 v86, v77, v77
	s_waitcnt vmcnt(2)
	v_lshlrev_b32_e32 v134, 16, v25
	s_waitcnt vmcnt(1)
	v_lshlrev_b32_e32 v87, 16, v8
	v_and_b32_e32 v85, 0xffff0000, v8
	v_lshlrev_b32_e32 v82, 16, v9
	v_and_b32_e32 v83, 0xffff0000, v9
	global_load_dwordx2 v[30:31], v[0:1], off offset:-3584
	global_load_dwordx2 v[28:29], v[0:1], off offset:-3072
	global_load_dwordx2 v[8:9], v[0:1], off offset:-2560
	v_and_b32_e32 v135, 0xffff0000, v25
	v_mov_b32_e32 v139, v87
	s_waitcnt vmcnt(2)
	v_and_b32_e32 v149, 0xffff0000, v31
	v_and_b32_e32 v148, 0xffff0000, v30
	s_waitcnt vmcnt(0)
	v_lshlrev_b32_e32 v95, 16, v8
	v_and_b32_e32 v93, 0xffff0000, v8
	v_lshlrev_b32_e32 v90, 16, v9
	v_and_b32_e32 v91, 0xffff0000, v9
	global_load_dwordx2 v[10:11], v[0:1], off offset:-2048
	global_load_dwordx2 v[12:13], v[0:1], off offset:-1536
	global_load_dwordx2 v[8:9], v[0:1], off offset:-1024
	s_nop 0
	global_load_dwordx2 v[0:1], v[0:1], off offset:-512
	v_lshlrev_b32_e32 v147, 16, v31
	v_lshlrev_b32_e32 v146, 16, v30
	v_pk_mul_f32 v[30:31], v[148:149], v[148:149]
	v_mov_b32_e32 v141, v95
	v_pk_fma_f32 v[30:31], v[146:147], v[146:147], v[30:31]
	v_mov_b32_e32 v92, v95
	s_waitcnt vmcnt(2)
	v_and_b32_e32 v153, 0xffff0000, v13
	v_and_b32_e32 v152, 0xffff0000, v12
	s_waitcnt vmcnt(0)
;     ...
;             for (int j = 0; j < 4; ++j) { const v2u w = *(const v2u*)(upd2 + (size_t)r * DM + j * 256 + lane * 4); y[r][j][0] = bflo(w.x); y[r][j][1] = bfhi(w.x); y[r][j][2] = bflo(w.y); y[r][j][3] = bfhi(w.y); }
;         float rr[NR];
; #pragma unroll
;         for (int r = 0; r < NR; ++r) { float ss = 0.f;
; #pragma unroll
;             for (int j = 0; j < 4; ++j) ss += (y[r][j][0] * y[r][j][0] + y[r][j][1] * y[r][j][1]) + (y[r][j][2] * y[r][j][2] + y[r][j][3] * y[r][j][3]);
;             rr[r] = ss; }
	v_lshlrev_b32_e32 v127, 16, v0
	v_and_b32_e32 v125, 0xffff0000, v0
	v_lshlrev_b32_e32 v122, 16, v1
	v_and_b32_e32 v123, 0xffff0000, v1
	v_lshlrev_b32_e32 v0, 16, v2
	v_and_b32_e32 v1, 0xffff0000, v2
	v_lshlrev_b32_e32 v2, 16, v3
	v_and_b32_e32 v3, 0xffff0000, v3
	v_mul_f32_e32 v16, v3, v3
	v_mul_f32_e32 v4, v1, v1
	v_pk_fma_f32 v[20:21], v[2:3], v[2:3], v[16:17] op_sel_hi:[1,1,0]
	v_lshlrev_b32_e32 v17, 16, v19
	v_lshlrev_b32_e32 v16, 16, v18
	v_and_b32_e32 v19, 0xffff0000, v19
	v_and_b32_e32 v18, 0xffff0000, v18
	v_pk_fma_f32 v[4:5], v[0:1], v[0:1], v[4:5] op_sel_hi:[1,1,0]
	v_pk_mul_f32 v[26:27], v[18:19], v[18:19]
	v_mov_b32_e32 v80, v4
	v_mov_b32_e32 v132, v20
	v_pk_fma_f32 v[26:27], v[16:17], v[16:17], v[26:27]
	v_pk_add_f32 v[4:5], v[4:5], v[20:21]
	v_pk_mul_f32 v[20:21], v[80:81], v[132:133]
	v_mul_f32_e32 v80, v82, v82
	v_mov_b32_e32 v5, v21
	v_pk_add_f32 v[20:21], v[26:27], v[26:27] op_sel:[0,1] op_sel_hi:[1,0]
	v_mul_f32_e32 v26, v131, v131
	v_mov_b32_e32 v21, v78
	v_pk_add_f32 v[4:5], v[4:5], v[20:21]
	v_mul_f32_e32 v20, v129, v129
	v_pk_fma_f32 v[20:21], v[128:129], v[128:129], v[20:21] op_sel_hi:[1,1,0]
	v_pk_fma_f32 v[26:27], v[130:131], v[130:131], v[26:27] op_sel_hi:[1,1,0]
	v_mov_b32_e32 v21, v84
	v_mov_b32_e32 v27, v86
	v_pk_add_f32 v[20:21], v[20:21], v[26:27]
	v_mul_f32_e32 v78, v85, v85
	v_pk_add_f32 v[144:145], v[4:5], v[20:21]
	v_lshlrev_b32_e32 v4, 16, v6
	v_and_b32_e32 v5, 0xffff0000, v6
	v_lshlrev_b32_e32 v6, 16, v7
	v_and_b32_e32 v7, 0xffff0000, v7
	v_mul_f32_e32 v20, v7, v7
	v_pk_fma_f32 v[26:27], v[6:7], v[6:7], v[20:21] op_sel_hi:[1,1,0]
	v_lshlrev_b32_e32 v21, 16, v23
	v_lshlrev_b32_e32 v20, 16, v22
	v_and_b32_e32 v23, 0xffff0000, v23
	v_and_b32_e32 v22, 0xffff0000, v22
	v_pk_mul_f32 v[132:133], v[22:23], v[22:23]
	v_mov_b32_e32 v138, v26
	v_pk_fma_f32 v[136:137], v[20:21], v[20:21], v[132:133]
	v_lshlrev_b32_e32 v132, 16, v24
	v_and_b32_e32 v133, 0xffff0000, v24
	v_mul_f32_e32 v24, v5, v5
	v_pk_fma_f32 v[24:25], v[4:5], v[4:5], v[24:25] op_sel_hi:[1,1,0]
	v_mul_f32_e32 v84, v83, v83
	v_mov_b32_e32 v86, v24
	v_pk_add_f32 v[24:25], v[24:25], v[26:27]
	v_pk_mul_f32 v[26:27], v[86:87], v[138:139]
	v_lshlrev_b32_e32 v138, 16, v29
	v_mov_b32_e32 v25, v27
	v_pk_add_f32 v[26:27], v[136:137], v[136:137] op_sel:[0,1] op_sel_hi:[1,0]
	v_and_b32_e32 v139, 0xffff0000, v29
	v_mov_b32_e32 v27, v78
	v_pk_add_f32 v[24:25], v[24:25], v[26:27]
	v_mul_f32_e32 v26, v133, v133
	v_mul_f32_e32 v78, v135, v135
	v_pk_fma_f32 v[26:27], v[132:133], v[132:133], v[26:27] op_sel_hi:[1,1,0]
	v_pk_fma_f32 v[136:137], v[134:135], v[134:135], v[78:79] op_sel_hi:[1,1,0]
	v_mov_b32_e32 v27, v80
	v_mov_b32_e32 v137, v84
	v_pk_add_f32 v[26:27], v[26:27], v[136:137]
	v_lshlrev_b32_e32 v136, 16, v28
	v_pk_add_f32 v[154:155], v[24:25], v[26:27]
	v_and_b32_e32 v25, 0xffff0000, v14
	v_and_b32_e32 v27, 0xffff0000, v15
	v_lshlrev_b32_e32 v24, 16, v14
	v_lshlrev_b32_e32 v26, 16, v15
	v_mul_f32_e32 v14, v27, v27
	v_and_b32_e32 v137, 0xffff0000, v28
	v_mul_f32_e32 v28, v25, v25
	v_pk_fma_f32 v[14:15], v[26:27], v[26:27], v[14:15] op_sel_hi:[1,1,0]
	v_pk_fma_f32 v[28:29], v[24:25], v[24:25], v[28:29] op_sel_hi:[1,1,0]
	v_mov_b32_e32 v140, v14
	v_mov_b32_e32 v94, v28
	v_pk_add_f32 v[14:15], v[28:29], v[14:15]
	v_pk_mul_f32 v[28:29], v[94:95], v[140:141]
	v_mul_f32_e32 v78, v93, v93
	v_mov_b32_e32 v15, v29
	v_pk_add_f32 v[28:29], v[30:31], v[30:31] op_sel:[0,1] op_sel_hi:[1,0]
	v_mul_f32_e32 v30, v139, v139
	v_mov_b32_e32 v29, v78
	v_pk_add_f32 v[14:15], v[14:15], v[28:29]
	v_mul_f32_e32 v28, v137, v137
	v_mul_f32_e32 v80, v90, v90
	v_mul_f32_e32 v84, v91, v91
	v_pk_fma_f32 v[28:29], v[136:137], v[136:137], v[28:29] op_sel_hi:[1,1,0]
	v_pk_fma_f32 v[30:31], v[138:139], v[138:139], v[30:31] op_sel_hi:[1,1,0]
	v_mov_b32_e32 v29, v80
	v_mov_b32_e32 v31, v84
	v_pk_add_f32 v[28:29], v[28:29], v[30:31]
	v_and_b32_e32 v31, 0xffff0000, v11
	v_pk_add_f32 v[14:15], v[14:15], v[28:29]
	v_and_b32_e32 v29, 0xffff0000, v10
	v_lshlrev_b32_e32 v28, 16, v10
	v_lshlrev_b32_e32 v30, 16, v11
	v_mul_f32_e32 v10, v31, v31
	v_lshlrev_b32_e32 v140, 16, v8
	v_and_b32_e32 v141, 0xffff0000, v8
	v_mul_f32_e32 v8, v29, v29
	v_pk_fma_f32 v[10:11], v[30:31], v[30:31], v[10:11] op_sel_hi:[1,1,0]
	v_lshlrev_b32_e32 v142, 16, v9
	v_and_b32_e32 v143, 0xffff0000, v9
	v_pk_fma_f32 v[8:9], v[28:29], v[28:29], v[8:9] op_sel_hi:[1,1,0]
	v_lshlrev_b32_e32 v151, 16, v13
	v_lshlrev_b32_e32 v150, 16, v12
	v_pk_mul_f32 v[12:13], v[152:153], v[152:153]
	v_mov_b32_e32 v126, v8
	v_mov_b32_e32 v162, v10
	v_mov_b32_e32 v163, v127
	v_pk_fma_f32 v[12:13], v[150:151], v[150:151], v[12:13]
	v_pk_add_f32 v[8:9], v[8:9], v[10:11]
	v_pk_mul_f32 v[10:11], v[126:127], v[162:163]
	v_mul_f32_e32 v78, v125, v125
	v_mov_b32_e32 v9, v11
	v_pk_add_f32 v[10:11], v[12:13], v[12:13] op_sel:[0,1] op_sel_hi:[1,0]
	v_mul_f32_e32 v12, v143, v143
	v_mov_b32_e32 v11, v78
	v_pk_add_f32 v[8:9], v[8:9], v[10:11]
	v_mul_f32_e32 v10, v141, v141
	v_mul_f32_e32 v80, v122, v122
	v_mul_f32_e32 v84, v123, v123
	v_pk_fma_f32 v[10:11], v[140:141], v[140:141], v[10:11] op_sel_hi:[1,1,0]
	v_pk_fma_f32 v[12:13], v[142:143], v[142:143], v[12:13] op_sel_hi:[1,1,0]
	v_mov_b32_e32 v11, v80
	v_mov_b32_e32 v13, v84
	v_pk_add_f32 v[10:11], v[10:11], v[12:13]
	v_mov_b32_e32 v78, v81
	v_pk_add_f32 v[8:9], v[8:9], v[10:11]
	v_mov_b32_e32 v10, v154
	v_mov_b32_e32 v11, v144
	v_mov_b32_e32 v144, v155
	v_pk_add_f32 v[10:11], v[10:11], v[144:145]
	ds_bpermute_b32 v13, v161, v11
	ds_bpermute_b32 v12, v161, v10
	v_lshl_add_u64 v[144:145], v[96:97], 0, s[4:5]
	s_movk_i32 s4, 0x5000
	v_lshl_add_u64 v[154:155], s[10:11], 0, v[66:67]
	v_mov_b32_e32 v124, v127
	s_waitcnt lgkmcnt(0)
;     ...
;         for (int r = 0; r < NR; ++r) rr[r] = rsqrtf(wave_sum(rr[r]) * (1.f / 1024.f) + EPSN);
; #pragma unroll
;         for (int j = 0; j < 4; ++j) { const f32x4 g = *(const f32x4*)(gate2 + j * 256 + lane * 4) * *(const f32x4*)(gupd2 + j * 256 + lane * 4);
; #pragma unroll
;             for (int r = 0; r < NR; ++r) x[r][j] = x[r][j] + g * (y[r][j] * rr[r]); }
	v_pk_add_f32 v[10:11], v[10:11], v[12:13]
	ds_bpermute_b32 v13, v160, v11
	ds_bpermute_b32 v12, v160, v10
	s_waitcnt lgkmcnt(0)
	v_pk_add_f32 v[10:11], v[10:11], v[12:13]
	ds_bpermute_b32 v13, v159, v11
	ds_bpermute_b32 v12, v159, v10
	s_waitcnt lgkmcnt(0)
	v_pk_add_f32 v[10:11], v[10:11], v[12:13]
	ds_bpermute_b32 v13, v158, v11
	ds_bpermute_b32 v12, v158, v10
	s_waitcnt lgkmcnt(0)
	v_pk_add_f32 v[10:11], v[10:11], v[12:13]
	ds_bpermute_b32 v13, v157, v11
	ds_bpermute_b32 v12, v157, v10
	s_waitcnt lgkmcnt(0)
	v_pk_add_f32 v[10:11], v[10:11], v[12:13]
	ds_bpermute_b32 v13, v156, v11
	ds_bpermute_b32 v12, v156, v10
	s_waitcnt lgkmcnt(0)
	v_pk_add_f32 v[10:11], v[10:11], v[12:13]
	s_nop 0
	v_pk_fma_f32 v[10:11], v[10:11], s[72:73], v[88:89] op_sel_hi:[1,0,0]
	s_nop 0
	v_mul_f32_e32 v12, 0x4b800000, v11
	v_cmp_gt_f32_e64 s[6:7], s29, v11
	v_cmp_gt_f32_e32 vcc, s29, v10
	s_nop 0
	v_cndmask_b32_e64 v11, v11, v12, s[6:7]
	v_rsq_f32_e32 v11, v11
	s_nop 0
	v_mul_f32_e32 v12, 0x45800000, v11
	v_cndmask_b32_e64 v84, v11, v12, s[6:7]
	v_mul_f32_e32 v11, 0x4b800000, v10
	v_cndmask_b32_e32 v10, v10, v11, vcc
	v_rsq_f32_e32 v10, v10
	v_pk_mul_f32 v[0:1], v[84:85], v[0:1] op_sel_hi:[0,1]
	v_pk_mul_f32 v[2:3], v[84:85], v[2:3] op_sel_hi:[0,1]
	v_mul_f32_e32 v11, 0x45800000, v10
	v_cndmask_b32_e32 v80, v10, v11, vcc
	v_mov_b32_e32 v10, v8
	v_mov_b32_e32 v11, v14
	v_mov_b32_e32 v14, v9
	v_pk_add_f32 v[8:9], v[10:11], v[14:15]
	ds_bpermute_b32 v11, v161, v9
	ds_bpermute_b32 v10, v161, v8
	s_waitcnt lgkmcnt(0)
	v_pk_add_f32 v[8:9], v[8:9], v[10:11]
	ds_bpermute_b32 v11, v160, v9
	ds_bpermute_b32 v10, v160, v8
	s_waitcnt lgkmcnt(0)
	v_pk_add_f32 v[8:9], v[8:9], v[10:11]
	ds_bpermute_b32 v11, v159, v9
	ds_bpermute_b32 v10, v159, v8
	s_waitcnt lgkmcnt(0)
	v_pk_add_f32 v[8:9], v[8:9], v[10:11]
	ds_bpermute_b32 v11, v158, v9
	ds_bpermute_b32 v10, v158, v8
	s_waitcnt lgkmcnt(0)
	v_pk_add_f32 v[8:9], v[8:9], v[10:11]
	ds_bpermute_b32 v11, v157, v9
	ds_bpermute_b32 v10, v157, v8
	s_waitcnt lgkmcnt(0)
	v_pk_add_f32 v[8:9], v[8:9], v[10:11]
	ds_bpermute_b32 v11, v156, v9
	ds_bpermute_b32 v10, v156, v8
	s_waitcnt lgkmcnt(0)
	v_pk_add_f32 v[8:9], v[8:9], v[10:11]
	s_nop 0
	v_pk_fma_f32 v[8:9], v[8:9], s[72:73], v[88:89] op_sel_hi:[1,0,0]
	s_nop 0
	v_mul_f32_e32 v10, 0x4b800000, v9
	v_cmp_gt_f32_e64 s[6:7], s29, v9
	v_cmp_gt_f32_e32 vcc, s29, v8
	s_nop 0
	v_cndmask_b32_e64 v9, v9, v10, s[6:7]
	v_rsq_f32_e32 v9, v9
	s_nop 0
	v_mul_f32_e32 v10, 0x45800000, v9
	v_cndmask_b32_e64 v88, v9, v10, s[6:7]
	v_mul_f32_e32 v9, 0x4b800000, v8
	v_cndmask_b32_e32 v8, v8, v9, vcc
	v_rsq_f32_e32 v8, v8
	s_nop 0
	v_mul_f32_e32 v9, 0x45800000, v8
	v_cndmask_b32_e32 v86, v8, v9, vcc
	v_add_co_u32_e32 v8, vcc, s4, v96
	v_readlane_b32 s4, v253, 38
	s_nop 0
	v_addc_co_u32_e32 v9, vcc, 0, v97, vcc
	global_load_dwordx4 v[8:11], v[8:9], off
	s_nop 0
	global_load_dwordx4 v[12:15], v[154:155], off
	v_readlane_b32 s5, v253, 39
	s_andn2_b64 vcc, exec, s[4:5]
	s_waitcnt vmcnt(0)
	v_pk_mul_f32 v[96:97], v[10:11], v[14:15]
	v_pk_mul_f32 v[162:163], v[8:9], v[12:13]
	v_pk_fma_f32 v[14:15], v[2:3], v[96:97], v[98:99]
	v_pk_fma_f32 v[12:13], v[0:1], v[162:163], v[48:49]
	v_pk_mul_f32 v[0:1], v[80:81], v[4:5] op_sel_hi:[0,1]
	v_pk_mul_f32 v[2:3], v[80:81], v[6:7] op_sel_hi:[0,1]
	v_pk_fma_f32 v[10:11], v[2:3], v[96:97], v[100:101]
	v_pk_fma_f32 v[8:9], v[0:1], v[162:163], v[50:51]
	v_pk_mul_f32 v[0:1], v[88:89], v[24:25] op_sel_hi:[0,1]
	v_pk_mul_f32 v[2:3], v[88:89], v[26:27] op_sel_hi:[0,1]
	v_pk_fma_f32 v[6:7], v[96:97], v[2:3], v[102:103]
	v_pk_fma_f32 v[4:5], v[162:163], v[0:1], v[52:53]
	v_pk_mul_f32 v[0:1], v[86:87], v[28:29] op_sel_hi:[0,1]
	v_pk_mul_f32 v[2:3], v[86:87], v[30:31] op_sel_hi:[0,1]
	global_load_dwordx4 v[24:27], v[144:145], off offset:1024
	global_load_dwordx4 v[28:31], v[154:155], off offset:1024
	v_pk_fma_f32 v[0:1], v[162:163], v[0:1], v[54:55]
	v_pk_fma_f32 v[2:3], v[96:97], v[2:3], v[104:105]
	s_waitcnt vmcnt(0)
;     ...
;         for (int j = 0; j < 4; ++j) { const f32x4 g = *(const f32x4*)(gate2 + j * 256 + lane * 4) * *(const f32x4*)(gupd2 + j * 256 + lane * 4);
; #pragma unroll
;             for (int r = 0; r < NR; ++r) x[r][j] = x[r][j] + g * (y[r][j] * rr[r]); }
;     }
;     if (xout) {
; #pragma unroll
;         for (int r = 0; r < NR; ++r)
; #pragma unroll
;             for (int j = 0; j < 4; ++j) *(f32x4*)(xout + (size_t)r * DM + j * 256 + lane * 4) = x[r][j];
	v_pk_mul_f32 v[50:51], v[24:25], v[28:29]
	v_mov_b32_e32 v25, v18
	v_mov_b32_e32 v18, v17
	v_pk_mul_f32 v[48:49], v[26:27], v[30:31]
	v_mov_b32_e32 v24, v16
	v_pk_mul_f32 v[16:17], v[84:85], v[18:19] op_sel_hi:[0,1]
	v_pk_fma_f32 v[30:31], v[16:17], v[48:49], v[106:107]
	v_mov_b32_e32 v16, v20
	v_mov_b32_e32 v17, v22
	v_pk_mul_f32 v[24:25], v[84:85], v[24:25] op_sel_hi:[0,1]
	v_pk_mul_f32 v[16:17], v[80:81], v[16:17] op_sel_hi:[0,1]
	v_pk_fma_f32 v[28:29], v[24:25], v[50:51], v[32:33]
	v_pk_fma_f32 v[24:25], v[16:17], v[50:51], v[34:35]
	v_mov_b32_e32 v16, v146
	v_mov_b32_e32 v17, v148
	v_pk_mul_f32 v[16:17], v[88:89], v[16:17] op_sel_hi:[0,1]
	v_mov_b32_e32 v22, v21
	v_pk_fma_f32 v[20:21], v[50:51], v[16:17], v[36:37]
	v_mov_b32_e32 v16, v150
	v_mov_b32_e32 v17, v152
	v_pk_mul_f32 v[16:17], v[86:87], v[16:17] op_sel_hi:[0,1]
	v_pk_fma_f32 v[16:17], v[50:51], v[16:17], v[38:39]
	global_load_dwordx4 v[32:35], v[144:145], off offset:2048
	global_load_dwordx4 v[36:39], v[154:155], off offset:2048
	v_pk_mul_f32 v[18:19], v[80:81], v[22:23] op_sel_hi:[0,1]
	v_mov_b32_e32 v148, v147
	v_pk_fma_f32 v[26:27], v[18:19], v[48:49], v[44:45]
	v_pk_mul_f32 v[18:19], v[88:89], v[148:149] op_sel_hi:[0,1]
	v_mov_b32_e32 v152, v151
	v_pk_fma_f32 v[22:23], v[48:49], v[18:19], v[46:47]
	v_pk_mul_f32 v[18:19], v[86:87], v[152:153] op_sel_hi:[0,1]
	v_pk_fma_f32 v[18:19], v[48:49], v[18:19], v[40:41]
	v_pk_mul_f32 v[48:49], v[86:87], v[140:141] op_sel_hi:[0,1]
	v_pk_mul_f32 v[50:51], v[86:87], v[142:143] op_sel_hi:[0,1]
	s_waitcnt vmcnt(0)
	v_pk_mul_f32 v[34:35], v[34:35], v[38:39]
	v_pk_mul_f32 v[32:33], v[32:33], v[36:37]
	v_pk_mul_f32 v[36:37], v[84:85], v[128:129] op_sel_hi:[0,1]
	v_pk_mul_f32 v[38:39], v[84:85], v[130:131] op_sel_hi:[0,1]
	v_pk_fma_f32 v[46:47], v[38:39], v[34:35], v[114:115]
	v_pk_fma_f32 v[44:45], v[36:37], v[32:33], v[42:43]
	v_pk_mul_f32 v[36:37], v[80:81], v[132:133] op_sel_hi:[0,1]
	v_pk_mul_f32 v[38:39], v[80:81], v[134:135] op_sel_hi:[0,1]
	v_pk_fma_f32 v[42:43], v[38:39], v[34:35], v[116:117]
	v_pk_fma_f32 v[40:41], v[36:37], v[32:33], v[108:109]
	v_pk_mul_f32 v[36:37], v[88:89], v[136:137] op_sel_hi:[0,1]
	v_pk_mul_f32 v[38:39], v[88:89], v[138:139] op_sel_hi:[0,1]
	v_pk_fma_f32 v[38:39], v[38:39], v[34:35], v[118:119]
	v_pk_fma_f32 v[36:37], v[36:37], v[32:33], v[110:111]
	v_pk_fma_f32 v[34:35], v[34:35], v[50:51], v[120:121]
	v_pk_fma_f32 v[32:33], v[32:33], v[48:49], v[112:113]
	global_load_dwordx4 v[48:51], v[144:145], off offset:3072
	global_load_dwordx4 v[52:55], v[154:155], off offset:3072
	s_waitcnt vmcnt(0)
	v_pk_mul_f32 v[50:51], v[50:51], v[54:55]
	v_pk_mul_f32 v[48:49], v[48:49], v[52:53]
	v_pk_mul_f32 v[52:53], v[84:85], v[78:79] op_sel_hi:[0,1]
	v_pk_mul_f32 v[54:55], v[84:85], v[76:77] op_sel_hi:[0,1]
	v_mov_b32_e32 v84, v87
	v_pk_fma_f32 v[62:63], v[54:55], v[50:51], v[62:63]
	v_pk_fma_f32 v[60:61], v[52:53], v[48:49], v[60:61]
	v_pk_mul_f32 v[52:53], v[80:81], v[84:85] op_sel_hi:[0,1]
	v_pk_mul_f32 v[54:55], v[80:81], v[82:83] op_sel_hi:[0,1]
	v_pk_fma_f32 v[58:59], v[54:55], v[50:51], v[58:59]
	v_pk_fma_f32 v[56:57], v[52:53], v[48:49], v[56:57]
	v_pk_mul_f32 v[52:53], v[88:89], v[92:93] op_sel_hi:[0,1]
	v_pk_mul_f32 v[54:55], v[88:89], v[90:91] op_sel_hi:[0,1]
	v_pk_fma_f32 v[54:55], v[54:55], v[50:51], v[74:75]
	v_pk_fma_f32 v[52:53], v[52:53], v[48:49], v[72:73]
	v_pk_mul_f32 v[72:73], v[86:87], v[124:125] op_sel_hi:[0,1]
	v_pk_mul_f32 v[74:75], v[86:87], v[122:123] op_sel_hi:[0,1]
	v_pk_fma_f32 v[50:51], v[50:51], v[74:75], v[70:71]
	v_pk_fma_f32 v[48:49], v[48:49], v[72:73], v[68:69]
	s_cbranch_vccnz .LBB0_877
	s_add_u32 s4, s12, s78
	s_addc_u32 s5, s13, s79
	v_lshl_add_u64 v[68:69], s[4:5], 0, v[66:67]
	v_add_co_u32_e32 v70, vcc, 0x1000, v68
	global_store_dwordx4 v[68:69], v[12:15], off
	global_store_dwordx4 v[68:69], v[28:31], off offset:1024
	global_store_dwordx4 v[68:69], v[44:47], off offset:2048
	global_store_dwordx4 v[68:69], v[60:63], off offset:3072
	v_addc_co_u32_e32 v71, vcc, 0, v69, vcc
	global_store_dwordx4 v[70:71], v[8:11], off
	global_store_dwordx4 v[70:71], v[24:27], off offset:1024
	global_store_dwordx4 v[70:71], v[40:43], off offset:2048
	global_store_dwordx4 v[70:71], v[56:59], off offset:3072
	v_add_co_u32_e32 v70, vcc, 0x2000, v68
	s_nop 1
	v_addc_co_u32_e32 v71, vcc, 0, v69, vcc
	v_add_co_u32_e32 v68, vcc, 0x3000, v68
	global_store_dwordx4 v[70:71], v[4:7], off
	global_store_dwordx4 v[70:71], v[20:23], off offset:1024
	global_store_dwordx4 v[70:71], v[36:39], off offset:2048
	global_store_dwordx4 v[70:71], v[52:55], off offset:3072
	v_addc_co_u32_e32 v69, vcc, 0, v69, vcc
	global_store_dwordx4 v[68:69], v[0:3], off
	global_store_dwordx4 v[68:69], v[16:19], off offset:1024
	global_store_dwordx4 v[68:69], v[32:35], off offset:2048
	global_store_dwordx4 v[68:69], v[48:51], off offset:3072
